# spatial-gating chunk: second-half v loads and 15 norm-weight loads issued with the first loads at the chunk top (counted waits)
# baseline (speedup 1.0000x reference)
.LBB0_310:
	v_add_u32_e32 v0, s3, v117
	v_mad_i64_i32 v[8:9], s[24:25], v0, s9, v[82:83]
	s_barrier
	global_load_dwordx4 v[0:3], v[8:9], off offset:1264
	global_load_dwordx4 v[4:7], v[8:9], off offset:1248
	global_load_dwordx4 v[10:13], v[8:9], off offset:1232
	global_load_dwordx4 v[14:17], v[8:9], off offset:1216
	global_load_dwordx4 v[214:217], v[8:9], off offset:1328
	global_load_dwordx4 v[218:221], v[8:9], off offset:1312
	global_load_dwordx4 v[222:225], v[8:9], off offset:1296
	global_load_dwordx4 v[226:229], v[8:9], off offset:1280
	global_load_dwordx4 v[94:97], v[66:67], off offset:48
	global_load_dwordx4 v[98:101], v[66:67], off offset:32
	global_load_dwordx4 v[102:105], v[66:67], off offset:16
	global_load_dwordx4 v[106:109], v[66:67], off
	global_load_dwordx4 v[110:113], v[66:67], off offset:112
	global_load_dwordx4 v[120:123], v[66:67], off offset:96
	global_load_dwordx4 v[124:127], v[66:67], off offset:80
	global_load_dwordx4 v[128:131], v[66:67], off offset:64
	global_load_dwordx4 v[132:135], v[66:67], off offset:176
	global_load_dwordx4 v[136:139], v[66:67], off offset:160
	global_load_dwordx4 v[140:143], v[66:67], off offset:144
	global_load_dwordx4 v[144:147], v[66:67], off offset:128
	global_load_dwordx4 v[148:151], v[66:67], off offset:224
	global_load_dwordx4 v[152:155], v[66:67], off offset:208
	global_load_dwordx4 v[162:165], v[66:67], off offset:192
	s_add_i32 s7, s7, s18
	s_waitcnt vmcnt(19)
	v_lshlrev_b32_e32 v18, 16, v14
	v_mul_f32_e32 v19, 0x3d372713, v18
	v_mul_f32_e32 v19, v19, v18
	v_fma_f32 v19, v19, v18, v18
	v_mul_f32_e32 v19, 0x3f4c422a, v19
	v_mul_f32_e32 v19, -2.0, v19
	v_mul_f32_e32 v19, 0x3fb8aa3b, v19
	v_exp_f32_e32 v19, v19
	v_and_b32_e32 v14, 0xffff0000, v14
	v_add_f32_e32 v19, 1.0, v19
	v_rcp_f32_e32 v19, v19
	s_nop 0
	v_mul_f32_e32 v24, v19, v18
	v_mul_f32_e32 v18, 0x3d372713, v14
	v_mul_f32_e32 v18, v18, v14
	v_fma_f32 v18, v18, v14, v14
	v_mul_f32_e32 v18, 0x3f4c422a, v18
	v_mul_f32_e32 v18, -2.0, v18
	v_mul_f32_e32 v18, 0x3fb8aa3b, v18
	v_exp_f32_e32 v18, v18
	s_nop 0
	v_add_f32_e32 v18, 1.0, v18
	v_rcp_f32_e32 v18, v18
	s_nop 0
	v_mul_f32_e32 v25, v18, v14
	v_lshlrev_b32_e32 v18, 16, v15
	v_mul_f32_e32 v19, 0x3d372713, v18
	v_mul_f32_e32 v19, v19, v18
	v_fma_f32 v19, v19, v18, v18
	v_mul_f32_e32 v19, 0x3f4c422a, v19
	v_mul_f32_e32 v19, -2.0, v19
	v_mul_f32_e32 v19, 0x3fb8aa3b, v19
	v_exp_f32_e32 v19, v19
	v_and_b32_e32 v15, 0xffff0000, v15
	v_mul_f32_e32 v14, v25, v25
	v_fmac_f32_e32 v14, v24, v24
	v_add_f32_e32 v19, 1.0, v19
	v_rcp_f32_e32 v19, v19
	s_nop 0
	v_mul_f32_e32 v26, v19, v18
	v_mul_f32_e32 v18, 0x3d372713, v15
	v_mul_f32_e32 v18, v18, v15
	v_fma_f32 v18, v18, v15, v15
	v_mul_f32_e32 v18, 0x3f4c422a, v18
	v_mul_f32_e32 v18, -2.0, v18
	v_mul_f32_e32 v18, 0x3fb8aa3b, v18
	v_exp_f32_e32 v18, v18
	s_nop 0
	v_add_f32_e32 v18, 1.0, v18
	v_rcp_f32_e32 v18, v18
	s_nop 0
	v_mul_f32_e32 v27, v18, v15
	v_mul_f32_e32 v15, v27, v27
	v_fmac_f32_e32 v15, v26, v26
	v_add_f32_e32 v14, v14, v15
	v_lshlrev_b32_e32 v15, 16, v16
	v_mul_f32_e32 v18, 0x3d372713, v15
	v_mul_f32_e32 v18, v18, v15
	v_fma_f32 v18, v18, v15, v15
	v_mul_f32_e32 v18, 0x3f4c422a, v18
	v_mul_f32_e32 v18, -2.0, v18
	v_mul_f32_e32 v18, 0x3fb8aa3b, v18
	v_exp_f32_e32 v18, v18
	s_nop 0
	v_add_f32_e32 v18, 1.0, v18
	v_rcp_f32_e32 v18, v18
	s_nop 0
	v_mul_f32_e32 v28, v18, v15
	v_and_b32_e32 v15, 0xffff0000, v16
	v_mul_f32_e32 v16, 0x3d372713, v15
	v_mul_f32_e32 v16, v16, v15
	v_fma_f32 v16, v16, v15, v15
	v_mul_f32_e32 v16, 0x3f4c422a, v16
	v_mul_f32_e32 v16, -2.0, v16
	v_mul_f32_e32 v16, 0x3fb8aa3b, v16
	v_exp_f32_e32 v16, v16
	s_nop 0
	v_add_f32_e32 v16, 1.0, v16
	v_rcp_f32_e32 v16, v16
	s_nop 0
	v_mul_f32_e32 v29, v16, v15
	v_mul_f32_e32 v15, v29, v29
	v_fmac_f32_e32 v15, v28, v28
	v_add_f32_e32 v14, v15, v14
	v_lshlrev_b32_e32 v15, 16, v17
	v_mul_f32_e32 v16, 0x3d372713, v15
	v_mul_f32_e32 v16, v16, v15
	v_fma_f32 v16, v16, v15, v15
	v_mul_f32_e32 v16, 0x3f4c422a, v16
	v_mul_f32_e32 v16, -2.0, v16
	v_mul_f32_e32 v16, 0x3fb8aa3b, v16
	v_exp_f32_e32 v16, v16
	s_nop 0
	v_add_f32_e32 v16, 1.0, v16
	v_rcp_f32_e32 v16, v16
	s_nop 0
	v_mul_f32_e32 v30, v16, v15
	v_and_b32_e32 v15, 0xffff0000, v17
	v_mul_f32_e32 v16, 0x3d372713, v15
	v_mul_f32_e32 v16, v16, v15
	v_fma_f32 v16, v16, v15, v15
	v_mul_f32_e32 v16, 0x3f4c422a, v16
	v_mul_f32_e32 v16, -2.0, v16
	v_mul_f32_e32 v16, 0x3fb8aa3b, v16
	v_exp_f32_e32 v16, v16
	s_nop 0
	v_add_f32_e32 v16, 1.0, v16
	v_rcp_f32_e32 v16, v16
	s_nop 0
	v_mul_f32_e32 v31, v16, v15
	v_mul_f32_e32 v15, v31, v31
	v_fmac_f32_e32 v15, v30, v30
	v_add_f32_e32 v14, v15, v14
	v_lshlrev_b32_e32 v15, 16, v10
	v_mul_f32_e32 v16, 0x3d372713, v15
	v_mul_f32_e32 v16, v16, v15
	v_fma_f32 v16, v16, v15, v15
	v_mul_f32_e32 v16, 0x3f4c422a, v16
	v_mul_f32_e32 v16, -2.0, v16
	v_mul_f32_e32 v16, 0x3fb8aa3b, v16
	v_exp_f32_e32 v16, v16
	v_and_b32_e32 v10, 0xffff0000, v10
	v_add_f32_e32 v16, 1.0, v16
	v_rcp_f32_e32 v16, v16
	s_nop 0
	v_mul_f32_e32 v32, v16, v15
	v_mul_f32_e32 v15, 0x3d372713, v10
	v_mul_f32_e32 v15, v15, v10
	v_fma_f32 v15, v15, v10, v10
	v_mul_f32_e32 v15, 0x3f4c422a, v15
	v_mul_f32_e32 v15, -2.0, v15
	v_mul_f32_e32 v15, 0x3fb8aa3b, v15
	v_exp_f32_e32 v15, v15
	s_nop 0
	v_add_f32_e32 v15, 1.0, v15
	v_rcp_f32_e32 v15, v15
	s_nop 0
	v_mul_f32_e32 v33, v15, v10
	v_mul_f32_e32 v10, v33, v33
	v_fmac_f32_e32 v10, v32, v32
	v_add_f32_e32 v10, v10, v14
	v_lshlrev_b32_e32 v14, 16, v11
	v_mul_f32_e32 v15, 0x3d372713, v14
	v_mul_f32_e32 v15, v15, v14
	v_fma_f32 v15, v15, v14, v14
	v_mul_f32_e32 v15, 0x3f4c422a, v15
	v_mul_f32_e32 v15, -2.0, v15
	v_mul_f32_e32 v15, 0x3fb8aa3b, v15
	v_exp_f32_e32 v15, v15
	v_and_b32_e32 v11, 0xffff0000, v11
	v_add_f32_e32 v15, 1.0, v15
	v_rcp_f32_e32 v15, v15
	s_nop 0
	v_mul_f32_e32 v34, v15, v14
	v_mul_f32_e32 v14, 0x3d372713, v11
	v_mul_f32_e32 v14, v14, v11
	v_fma_f32 v14, v14, v11, v11
	v_mul_f32_e32 v14, 0x3f4c422a, v14
	v_mul_f32_e32 v14, -2.0, v14
	v_mul_f32_e32 v14, 0x3fb8aa3b, v14
	v_exp_f32_e32 v14, v14
	s_nop 0
	v_add_f32_e32 v14, 1.0, v14
	v_rcp_f32_e32 v14, v14
	s_nop 0
	v_mul_f32_e32 v35, v14, v11
	v_mul_f32_e32 v11, v35, v35
	v_fmac_f32_e32 v11, v34, v34
	v_add_f32_e32 v10, v11, v10
	v_lshlrev_b32_e32 v11, 16, v12
	v_mul_f32_e32 v14, 0x3d372713, v11
	v_mul_f32_e32 v14, v14, v11
	v_fma_f32 v14, v14, v11, v11
	v_mul_f32_e32 v14, 0x3f4c422a, v14
	v_mul_f32_e32 v14, -2.0, v14
	v_mul_f32_e32 v14, 0x3fb8aa3b, v14
	v_exp_f32_e32 v14, v14
	s_nop 0
	v_add_f32_e32 v14, 1.0, v14
	v_rcp_f32_e32 v14, v14
	s_nop 0
	v_mul_f32_e32 v36, v14, v11
	v_and_b32_e32 v11, 0xffff0000, v12
	v_mul_f32_e32 v12, 0x3d372713, v11
	v_mul_f32_e32 v12, v12, v11
	v_fma_f32 v12, v12, v11, v11
	v_mul_f32_e32 v12, 0x3f4c422a, v12
	v_mul_f32_e32 v12, -2.0, v12
	v_mul_f32_e32 v12, 0x3fb8aa3b, v12
	v_exp_f32_e32 v12, v12
	s_nop 0
	v_add_f32_e32 v12, 1.0, v12
	v_rcp_f32_e32 v12, v12
	s_nop 0
	v_mul_f32_e32 v37, v12, v11
	v_mul_f32_e32 v11, v37, v37
	v_fmac_f32_e32 v11, v36, v36
	v_add_f32_e32 v10, v11, v10
	v_lshlrev_b32_e32 v11, 16, v13
	v_mul_f32_e32 v12, 0x3d372713, v11
	v_mul_f32_e32 v12, v12, v11
	v_fma_f32 v12, v12, v11, v11
	v_mul_f32_e32 v12, 0x3f4c422a, v12
	v_mul_f32_e32 v12, -2.0, v12
	v_mul_f32_e32 v12, 0x3fb8aa3b, v12
	v_exp_f32_e32 v12, v12
	s_nop 0
	v_add_f32_e32 v12, 1.0, v12
	v_rcp_f32_e32 v12, v12
	s_nop 0
	v_mul_f32_e32 v38, v12, v11
	v_and_b32_e32 v11, 0xffff0000, v13
	v_mul_f32_e32 v12, 0x3d372713, v11
	v_mul_f32_e32 v12, v12, v11
	v_fma_f32 v12, v12, v11, v11
	v_mul_f32_e32 v12, 0x3f4c422a, v12
	v_mul_f32_e32 v12, -2.0, v12
	v_mul_f32_e32 v12, 0x3fb8aa3b, v12
	v_exp_f32_e32 v12, v12
	s_nop 0
	v_add_f32_e32 v12, 1.0, v12
	v_rcp_f32_e32 v12, v12
	s_nop 0
	v_mul_f32_e32 v39, v12, v11
	v_mul_f32_e32 v11, v39, v39
	v_fmac_f32_e32 v11, v38, v38
	v_add_f32_e32 v10, v11, v10
	v_lshlrev_b32_e32 v11, 16, v4
	v_mul_f32_e32 v12, 0x3d372713, v11
	v_mul_f32_e32 v12, v12, v11
	v_fma_f32 v12, v12, v11, v11
	v_mul_f32_e32 v12, 0x3f4c422a, v12
	v_mul_f32_e32 v12, -2.0, v12
	v_mul_f32_e32 v12, 0x3fb8aa3b, v12
	v_exp_f32_e32 v12, v12
	v_and_b32_e32 v4, 0xffff0000, v4
	v_add_f32_e32 v12, 1.0, v12
	v_rcp_f32_e32 v12, v12
	s_nop 0
	v_mul_f32_e32 v40, v12, v11
	v_mul_f32_e32 v11, 0x3d372713, v4
	v_mul_f32_e32 v11, v11, v4
	v_fma_f32 v11, v11, v4, v4
	v_mul_f32_e32 v11, 0x3f4c422a, v11
	v_mul_f32_e32 v11, -2.0, v11
	v_mul_f32_e32 v11, 0x3fb8aa3b, v11
	v_exp_f32_e32 v11, v11
	s_nop 0
	v_add_f32_e32 v11, 1.0, v11
	v_rcp_f32_e32 v11, v11
	s_nop 0
	v_mul_f32_e32 v41, v11, v4
	v_mul_f32_e32 v4, v41, v41
	v_fmac_f32_e32 v4, v40, v40
	v_add_f32_e32 v4, v4, v10
	v_lshlrev_b32_e32 v10, 16, v5
	v_mul_f32_e32 v11, 0x3d372713, v10
	v_mul_f32_e32 v11, v11, v10
	v_fma_f32 v11, v11, v10, v10
	v_mul_f32_e32 v11, 0x3f4c422a, v11
	v_mul_f32_e32 v11, -2.0, v11
	v_mul_f32_e32 v11, 0x3fb8aa3b, v11
	v_exp_f32_e32 v11, v11
	v_and_b32_e32 v5, 0xffff0000, v5
	v_add_f32_e32 v11, 1.0, v11
	v_rcp_f32_e32 v11, v11
	s_nop 0
	v_mul_f32_e32 v42, v11, v10
	v_mul_f32_e32 v10, 0x3d372713, v5
	v_mul_f32_e32 v10, v10, v5
	v_fma_f32 v10, v10, v5, v5
	v_mul_f32_e32 v10, 0x3f4c422a, v10
	v_mul_f32_e32 v10, -2.0, v10
	v_mul_f32_e32 v10, 0x3fb8aa3b, v10
	v_exp_f32_e32 v10, v10
	s_nop 0
	v_add_f32_e32 v10, 1.0, v10
	v_rcp_f32_e32 v10, v10
	s_nop 0
	v_mul_f32_e32 v43, v10, v5
	v_mul_f32_e32 v5, v43, v43
	v_fmac_f32_e32 v5, v42, v42
	v_add_f32_e32 v4, v5, v4
	v_lshlrev_b32_e32 v5, 16, v6
	v_mul_f32_e32 v10, 0x3d372713, v5
	v_mul_f32_e32 v10, v10, v5
	v_fma_f32 v10, v10, v5, v5
	v_mul_f32_e32 v10, 0x3f4c422a, v10
	v_mul_f32_e32 v10, -2.0, v10
	v_mul_f32_e32 v10, 0x3fb8aa3b, v10
	v_exp_f32_e32 v10, v10
	s_nop 0
	v_add_f32_e32 v10, 1.0, v10
	v_rcp_f32_e32 v10, v10
	s_nop 0
	v_mul_f32_e32 v44, v10, v5
	v_and_b32_e32 v5, 0xffff0000, v6
	v_mul_f32_e32 v6, 0x3d372713, v5
	v_mul_f32_e32 v6, v6, v5
	v_fma_f32 v6, v6, v5, v5
	v_mul_f32_e32 v6, 0x3f4c422a, v6
	v_mul_f32_e32 v6, -2.0, v6
	v_mul_f32_e32 v6, 0x3fb8aa3b, v6
	v_exp_f32_e32 v6, v6
	s_nop 0
	v_add_f32_e32 v6, 1.0, v6
	v_rcp_f32_e32 v6, v6
	s_nop 0
	v_mul_f32_e32 v45, v6, v5
	v_mul_f32_e32 v5, v45, v45
	v_fmac_f32_e32 v5, v44, v44
	v_add_f32_e32 v4, v5, v4
	v_lshlrev_b32_e32 v5, 16, v7
	v_mul_f32_e32 v6, 0x3d372713, v5
	v_mul_f32_e32 v6, v6, v5
	v_fma_f32 v6, v6, v5, v5
	v_mul_f32_e32 v6, 0x3f4c422a, v6
	v_mul_f32_e32 v6, -2.0, v6
	v_mul_f32_e32 v6, 0x3fb8aa3b, v6
	v_exp_f32_e32 v6, v6
	s_nop 0
	v_add_f32_e32 v6, 1.0, v6
	v_rcp_f32_e32 v6, v6
	s_nop 0
	v_mul_f32_e32 v46, v6, v5
	v_and_b32_e32 v5, 0xffff0000, v7
	v_mul_f32_e32 v6, 0x3d372713, v5
	v_mul_f32_e32 v6, v6, v5
	v_fma_f32 v6, v6, v5, v5
	v_mul_f32_e32 v6, 0x3f4c422a, v6
	v_mul_f32_e32 v6, -2.0, v6
	v_mul_f32_e32 v6, 0x3fb8aa3b, v6
	v_exp_f32_e32 v6, v6
	s_nop 0
	v_add_f32_e32 v6, 1.0, v6
	v_rcp_f32_e32 v6, v6
	s_nop 0
	v_mul_f32_e32 v47, v6, v5
	v_mul_f32_e32 v5, v47, v47
	v_fmac_f32_e32 v5, v46, v46
	v_add_f32_e32 v4, v5, v4
	v_lshlrev_b32_e32 v5, 16, v0
	v_mul_f32_e32 v6, 0x3d372713, v5
	v_mul_f32_e32 v6, v6, v5
	v_fma_f32 v6, v6, v5, v5
	v_mul_f32_e32 v6, 0x3f4c422a, v6
	v_mul_f32_e32 v6, -2.0, v6
	v_mul_f32_e32 v6, 0x3fb8aa3b, v6
	v_exp_f32_e32 v6, v6
	v_and_b32_e32 v0, 0xffff0000, v0
	v_add_f32_e32 v6, 1.0, v6
	v_rcp_f32_e32 v6, v6
	s_nop 0
	v_mul_f32_e32 v48, v6, v5
	v_mul_f32_e32 v5, 0x3d372713, v0
	v_mul_f32_e32 v5, v5, v0
	v_fma_f32 v5, v5, v0, v0
	v_mul_f32_e32 v5, 0x3f4c422a, v5
	v_mul_f32_e32 v5, -2.0, v5
	v_mul_f32_e32 v5, 0x3fb8aa3b, v5
	v_exp_f32_e32 v5, v5
	s_nop 0
	v_add_f32_e32 v5, 1.0, v5
	v_rcp_f32_e32 v5, v5
	s_nop 0
	v_mul_f32_e32 v49, v5, v0
	v_mul_f32_e32 v0, v49, v49
	v_fmac_f32_e32 v0, v48, v48
	v_add_f32_e32 v0, v0, v4
	v_lshlrev_b32_e32 v4, 16, v1
	v_mul_f32_e32 v5, 0x3d372713, v4
	v_mul_f32_e32 v5, v5, v4
	v_fma_f32 v5, v5, v4, v4
	v_mul_f32_e32 v5, 0x3f4c422a, v5
	v_mul_f32_e32 v5, -2.0, v5
	v_mul_f32_e32 v5, 0x3fb8aa3b, v5
	v_exp_f32_e32 v5, v5
	v_and_b32_e32 v1, 0xffff0000, v1
	v_add_f32_e32 v5, 1.0, v5
	v_rcp_f32_e32 v5, v5
	s_nop 0
	v_mul_f32_e32 v50, v5, v4
	v_mul_f32_e32 v4, 0x3d372713, v1
	v_mul_f32_e32 v4, v4, v1
	v_fma_f32 v4, v4, v1, v1
	v_mul_f32_e32 v4, 0x3f4c422a, v4
	v_mul_f32_e32 v4, -2.0, v4
	v_mul_f32_e32 v4, 0x3fb8aa3b, v4
	v_exp_f32_e32 v4, v4
	s_nop 0
	v_add_f32_e32 v4, 1.0, v4
	v_rcp_f32_e32 v4, v4
	s_nop 0
	v_mul_f32_e32 v51, v4, v1
	v_mul_f32_e32 v1, v51, v51
	v_fmac_f32_e32 v1, v50, v50
	v_add_f32_e32 v0, v1, v0
	v_lshlrev_b32_e32 v1, 16, v2
	v_mul_f32_e32 v4, 0x3d372713, v1
	v_mul_f32_e32 v4, v4, v1
	v_fma_f32 v4, v4, v1, v1
	v_mul_f32_e32 v4, 0x3f4c422a, v4
	v_mul_f32_e32 v4, -2.0, v4
	v_mul_f32_e32 v4, 0x3fb8aa3b, v4
	v_exp_f32_e32 v4, v4
	s_nop 0
	v_add_f32_e32 v4, 1.0, v4
	v_rcp_f32_e32 v4, v4
	s_nop 0
	v_mul_f32_e32 v52, v4, v1
	v_and_b32_e32 v1, 0xffff0000, v2
	v_mul_f32_e32 v2, 0x3d372713, v1
	v_mul_f32_e32 v2, v2, v1
	v_fma_f32 v2, v2, v1, v1
	v_mul_f32_e32 v2, 0x3f4c422a, v2
	v_mul_f32_e32 v2, -2.0, v2
	v_mul_f32_e32 v2, 0x3fb8aa3b, v2
	v_exp_f32_e32 v2, v2
	s_nop 0
	v_add_f32_e32 v2, 1.0, v2
	v_rcp_f32_e32 v2, v2
	s_nop 0
	v_mul_f32_e32 v53, v2, v1
	v_mul_f32_e32 v1, v53, v53
	v_fmac_f32_e32 v1, v52, v52
	v_add_f32_e32 v0, v1, v0
	v_lshlrev_b32_e32 v1, 16, v3
	v_mul_f32_e32 v2, 0x3d372713, v1
	v_mul_f32_e32 v2, v2, v1
	v_fma_f32 v2, v2, v1, v1
	v_mul_f32_e32 v2, 0x3f4c422a, v2
	v_mul_f32_e32 v2, -2.0, v2
	v_mul_f32_e32 v2, 0x3fb8aa3b, v2
	v_exp_f32_e32 v2, v2
	s_nop 0
	v_add_f32_e32 v2, 1.0, v2
	v_rcp_f32_e32 v2, v2
	s_nop 0
	v_mul_f32_e32 v54, v2, v1
	v_and_b32_e32 v1, 0xffff0000, v3
	v_mul_f32_e32 v2, 0x3d372713, v1
	v_mul_f32_e32 v2, v2, v1
	v_fma_f32 v2, v2, v1, v1
	v_mul_f32_e32 v2, 0x3f4c422a, v2
	v_mul_f32_e32 v2, -2.0, v2
	v_mul_f32_e32 v2, 0x3fb8aa3b, v2
	v_exp_f32_e32 v2, v2
	s_nop 0
	v_add_f32_e32 v2, 1.0, v2
	v_rcp_f32_e32 v2, v2
	s_nop 0
	v_mul_f32_e32 v55, v2, v1
	v_mul_f32_e32 v1, v55, v55
	v_fmac_f32_e32 v1, v54, v54
	v_add_f32_e32 v18, v1, v0
	s_waitcnt vmcnt(15)
	v_mov_b32_e32 v0, v214
	v_mov_b32_e32 v1, v215
	v_mov_b32_e32 v2, v216
	v_mov_b32_e32 v3, v217
	v_mov_b32_e32 v4, v218
	v_mov_b32_e32 v5, v219
	v_mov_b32_e32 v6, v220
	v_mov_b32_e32 v7, v221
	v_mov_b32_e32 v10, v222
	v_mov_b32_e32 v11, v223
	v_mov_b32_e32 v12, v224
	v_mov_b32_e32 v13, v225
	v_mov_b32_e32 v14, v226
	v_mov_b32_e32 v15, v227
	v_mov_b32_e32 v16, v228
	v_mov_b32_e32 v17, v229
	v_lshlrev_b32_e32 v8, 16, v14
	v_mul_f32_e32 v9, 0x3d372713, v8
	v_mul_f32_e32 v9, v9, v8
	v_fma_f32 v9, v9, v8, v8
	v_mul_f32_e32 v9, 0x3f4c422a, v9
	v_mul_f32_e32 v9, -2.0, v9
	v_mul_f32_e32 v9, 0x3fb8aa3b, v9
	v_exp_f32_e32 v9, v9
	s_nop 0
	v_add_f32_e32 v9, 1.0, v9
	v_rcp_f32_e32 v9, v9
	s_nop 0
	v_mul_f32_e32 v56, v9, v8
	v_and_b32_e32 v8, 0xffff0000, v14
	v_mul_f32_e32 v9, 0x3d372713, v8
	v_mul_f32_e32 v9, v9, v8
	v_fma_f32 v9, v9, v8, v8
	v_mul_f32_e32 v9, 0x3f4c422a, v9
	v_mul_f32_e32 v9, -2.0, v9
	v_mul_f32_e32 v9, 0x3fb8aa3b, v9
	v_exp_f32_e32 v9, v9
	s_nop 0
	v_add_f32_e32 v9, 1.0, v9
	v_rcp_f32_e32 v9, v9
	s_nop 0
	v_mul_f32_e32 v57, v9, v8
	v_lshlrev_b32_e32 v9, 16, v15
	v_mul_f32_e32 v14, 0x3d372713, v9
	v_mul_f32_e32 v14, v14, v9
	v_fma_f32 v14, v14, v9, v9
	v_mul_f32_e32 v14, 0x3f4c422a, v14
	v_mul_f32_e32 v14, -2.0, v14
	v_mul_f32_e32 v14, 0x3fb8aa3b, v14
	v_exp_f32_e32 v14, v14
	v_mul_f32_e32 v8, v57, v57
	v_fmac_f32_e32 v8, v56, v56
	v_add_f32_e32 v8, v8, v18
	v_add_f32_e32 v14, 1.0, v14
	v_rcp_f32_e32 v14, v14
	s_nop 0
	v_mul_f32_e32 v58, v14, v9
	v_and_b32_e32 v9, 0xffff0000, v15
	v_mul_f32_e32 v14, 0x3d372713, v9
	v_mul_f32_e32 v14, v14, v9
	v_fma_f32 v14, v14, v9, v9
	v_mul_f32_e32 v14, 0x3f4c422a, v14
	v_mul_f32_e32 v14, -2.0, v14
	v_mul_f32_e32 v14, 0x3fb8aa3b, v14
	v_exp_f32_e32 v14, v14
	s_nop 0
	v_add_f32_e32 v14, 1.0, v14
	v_rcp_f32_e32 v14, v14
	s_nop 0
	v_mul_f32_e32 v59, v14, v9
	v_mul_f32_e32 v9, v59, v59
	v_fmac_f32_e32 v9, v58, v58
	v_add_f32_e32 v8, v9, v8
	v_lshlrev_b32_e32 v9, 16, v16
	v_mul_f32_e32 v14, 0x3d372713, v9
	v_mul_f32_e32 v14, v14, v9
	v_fma_f32 v14, v14, v9, v9
	v_mul_f32_e32 v14, 0x3f4c422a, v14
	v_mul_f32_e32 v14, -2.0, v14
	v_mul_f32_e32 v14, 0x3fb8aa3b, v14
	v_exp_f32_e32 v14, v14
	s_nop 0
	v_add_f32_e32 v14, 1.0, v14
	v_rcp_f32_e32 v14, v14
	s_nop 0
	v_mul_f32_e32 v60, v14, v9
	v_and_b32_e32 v9, 0xffff0000, v16
	v_mul_f32_e32 v14, 0x3d372713, v9
	v_mul_f32_e32 v14, v14, v9
	v_fma_f32 v14, v14, v9, v9
	v_mul_f32_e32 v14, 0x3f4c422a, v14
	v_mul_f32_e32 v14, -2.0, v14
	v_mul_f32_e32 v14, 0x3fb8aa3b, v14
	v_exp_f32_e32 v14, v14
	s_nop 0
	v_add_f32_e32 v14, 1.0, v14
	v_rcp_f32_e32 v14, v14
	s_nop 0
	v_mul_f32_e32 v61, v14, v9
	v_mul_f32_e32 v9, v61, v61
	v_fmac_f32_e32 v9, v60, v60
	v_add_f32_e32 v8, v9, v8
	v_lshlrev_b32_e32 v9, 16, v17
	v_mul_f32_e32 v14, 0x3d372713, v9
	v_mul_f32_e32 v14, v14, v9
	v_fma_f32 v14, v14, v9, v9
	v_mul_f32_e32 v14, 0x3f4c422a, v14
	v_mul_f32_e32 v14, -2.0, v14
	v_mul_f32_e32 v14, 0x3fb8aa3b, v14
	v_exp_f32_e32 v14, v14
	s_nop 0
	v_add_f32_e32 v14, 1.0, v14
	v_rcp_f32_e32 v14, v14
	s_nop 0
	v_mul_f32_e32 v62, v14, v9
	v_and_b32_e32 v9, 0xffff0000, v17
	v_mul_f32_e32 v14, 0x3d372713, v9
	v_mul_f32_e32 v14, v14, v9
	v_fma_f32 v14, v14, v9, v9
	v_mul_f32_e32 v14, 0x3f4c422a, v14
	v_mul_f32_e32 v14, -2.0, v14
	v_mul_f32_e32 v14, 0x3fb8aa3b, v14
	v_exp_f32_e32 v14, v14
	v_and_b32_e32 v17, 0xffff0000, v5
	v_add_f32_e32 v14, 1.0, v14
	v_rcp_f32_e32 v14, v14
	s_nop 0
	v_mul_f32_e32 v63, v14, v9
	v_mul_f32_e32 v9, v63, v63
	v_fmac_f32_e32 v9, v62, v62
	v_add_f32_e32 v8, v9, v8
	v_lshlrev_b32_e32 v9, 16, v10
	v_mul_f32_e32 v14, 0x3d372713, v9
	v_mul_f32_e32 v14, v14, v9
	v_fma_f32 v14, v14, v9, v9
	v_mul_f32_e32 v14, 0x3f4c422a, v14
	v_mul_f32_e32 v14, -2.0, v14
	v_mul_f32_e32 v14, 0x3fb8aa3b, v14
	v_exp_f32_e32 v14, v14
	s_nop 0
	v_add_f32_e32 v14, 1.0, v14
	v_rcp_f32_e32 v14, v14
	s_nop 0
	v_mul_f32_e32 v88, v14, v9
	v_and_b32_e32 v9, 0xffff0000, v10
	v_mul_f32_e32 v10, 0x3d372713, v9
	v_mul_f32_e32 v10, v10, v9
	v_fma_f32 v10, v10, v9, v9
	v_mul_f32_e32 v10, 0x3f4c422a, v10
	v_mul_f32_e32 v10, -2.0, v10
	v_mul_f32_e32 v10, 0x3fb8aa3b, v10
	v_exp_f32_e32 v10, v10
	s_nop 0
	v_add_f32_e32 v10, 1.0, v10
	v_rcp_f32_e32 v10, v10
	s_nop 0
	v_mul_f32_e32 v89, v10, v9
	v_mul_f32_e32 v9, v89, v89
	v_fmac_f32_e32 v9, v88, v88
	v_add_f32_e32 v8, v9, v8
	v_lshlrev_b32_e32 v9, 16, v11
	v_mul_f32_e32 v10, 0x3d372713, v9
	v_mul_f32_e32 v10, v10, v9
	v_fma_f32 v10, v10, v9, v9
	v_mul_f32_e32 v10, 0x3f4c422a, v10
	v_mul_f32_e32 v10, -2.0, v10
	v_mul_f32_e32 v10, 0x3fb8aa3b, v10
	v_exp_f32_e32 v10, v10
	s_nop 0
	v_add_f32_e32 v10, 1.0, v10
	v_rcp_f32_e32 v10, v10
	s_nop 0
	v_mul_f32_e32 v90, v10, v9
	v_and_b32_e32 v9, 0xffff0000, v11
	v_mul_f32_e32 v10, 0x3d372713, v9
	v_mul_f32_e32 v10, v10, v9
	v_fma_f32 v10, v10, v9, v9
	v_mul_f32_e32 v10, 0x3f4c422a, v10
	v_mul_f32_e32 v10, -2.0, v10
	v_mul_f32_e32 v10, 0x3fb8aa3b, v10
	v_exp_f32_e32 v10, v10
	s_nop 0
	v_add_f32_e32 v10, 1.0, v10
	v_rcp_f32_e32 v10, v10
	s_nop 0
	v_mul_f32_e32 v91, v10, v9
	v_mul_f32_e32 v9, v91, v91
	v_fmac_f32_e32 v9, v90, v90
	v_add_f32_e32 v16, v9, v8
	v_lshlrev_b32_e32 v8, 16, v12
	v_mul_f32_e32 v10, 0x3d372713, v8
	v_mul_f32_e32 v10, v10, v8
	v_mov_b32_e32 v11, v8
	v_fmac_f32_e32 v11, v10, v11
	v_and_b32_e32 v12, 0xffff0000, v12
	v_mul_f32_e32 v10, 0x3f4c422a, v11
	v_mul_f32_e32 v11, 0x3d372713, v12
	v_mul_f32_e32 v11, v11, v12
	v_mov_b32_e32 v14, v12
	v_fmac_f32_e32 v14, v11, v14
	v_mul_f32_e32 v11, 0x3f4c422a, v14
	v_mul_f32_e32 v11, -2.0, v11
	v_mul_f32_e32 v11, 0x3fb8aa3b, v11
	v_exp_f32_e32 v11, v11
	v_lshlrev_b32_e32 v9, 16, v13
	v_mov_b32_e32 v15, v9
	v_mul_f32_e32 v10, -2.0, v10
	v_add_f32_e32 v11, 1.0, v11
	v_rcp_f32_e32 v14, v11
	v_mul_f32_e32 v11, 0x3d372713, v9
	v_mul_f32_e32 v11, v11, v9
	v_fmac_f32_e32 v15, v11, v15
	v_mul_f32_e32 v11, 0x3f4c422a, v15
	v_mul_f32_e32 v11, -2.0, v11
	v_mul_f32_e32 v10, 0x3fb8aa3b, v10
	v_mul_f32_e32 v11, 0x3fb8aa3b, v11
	v_exp_f32_e32 v10, v10
	v_exp_f32_e32 v11, v11
	v_and_b32_e32 v13, 0xffff0000, v13
	v_add_f32_e32 v10, 1.0, v10
	v_add_f32_e32 v11, 1.0, v11
	v_rcp_f32_e32 v10, v10
	v_rcp_f32_e32 v11, v11
	s_nop 0
	v_pk_mul_f32 v[8:9], v[10:11], v[8:9]
	v_mul_f32_e32 v10, 0x3d372713, v13
	v_mul_f32_e32 v10, v10, v13
	v_mov_b32_e32 v11, v13
	v_fmac_f32_e32 v11, v10, v11
	v_mul_f32_e32 v10, 0x3f4c422a, v11
	v_mul_f32_e32 v10, -2.0, v10
	v_mul_f32_e32 v10, 0x3fb8aa3b, v10
	v_exp_f32_e32 v10, v10
	s_nop 0
	v_add_f32_e32 v10, 1.0, v10
	v_rcp_f32_e32 v15, v10
	s_nop 0
	v_pk_mul_f32 v[10:11], v[14:15], v[12:13]
	s_nop 0
	v_pk_mul_f32 v[12:13], v[10:11], v[10:11]
	s_nop 0
	v_pk_fma_f32 v[12:13], v[8:9], v[8:9], v[12:13]
	s_nop 0
	v_add_f32_e32 v12, v12, v16
	v_and_b32_e32 v16, 0xffff0000, v4
	v_add_f32_e32 v20, v13, v12
	v_lshlrev_b32_e32 v12, 16, v4
	v_mul_f32_e32 v4, 0x3d372713, v16
	v_lshlrev_b32_e32 v13, 16, v5
	v_mul_f32_e32 v4, v4, v16
	v_mov_b32_e32 v5, v16
	v_fmac_f32_e32 v5, v4, v5
	v_mul_f32_e32 v4, 0x3f4c422a, v5
	v_mul_f32_e32 v4, -2.0, v4
	v_mul_f32_e32 v4, 0x3fb8aa3b, v4
	v_exp_f32_e32 v4, v4
	v_mul_f32_e32 v14, 0x3d372713, v12
	v_mul_f32_e32 v14, v14, v12
	v_mov_b32_e32 v15, v12
	v_add_f32_e32 v4, 1.0, v4
	v_rcp_f32_e32 v18, v4
	v_mul_f32_e32 v4, 0x3d372713, v13
	v_mul_f32_e32 v4, v4, v13
	v_mov_b32_e32 v5, v13
	v_fmac_f32_e32 v15, v14, v15
	v_fmac_f32_e32 v5, v4, v5
	v_mul_f32_e32 v14, 0x3f4c422a, v15
	v_mul_f32_e32 v4, 0x3f4c422a, v5
	v_mul_f32_e32 v14, -2.0, v14
	v_mul_f32_e32 v4, -2.0, v4
	v_mul_f32_e32 v14, 0x3fb8aa3b, v14
	v_mul_f32_e32 v4, 0x3fb8aa3b, v4
	v_exp_f32_e32 v14, v14
	v_exp_f32_e32 v4, v4
	v_add_f32_e32 v14, 1.0, v14
	v_add_f32_e32 v4, 1.0, v4
	v_rcp_f32_e32 v14, v14
	v_rcp_f32_e32 v15, v4
	s_nop 0
	v_pk_mul_f32 v[4:5], v[14:15], v[12:13]
	v_mul_f32_e32 v12, 0x3d372713, v17
	v_mul_f32_e32 v12, v12, v17
	v_mov_b32_e32 v13, v17
	v_fmac_f32_e32 v13, v12, v13
	v_mul_f32_e32 v12, 0x3f4c422a, v13
	v_mul_f32_e32 v12, -2.0, v12
	v_mul_f32_e32 v12, 0x3fb8aa3b, v12
	v_exp_f32_e32 v12, v12
	s_nop 0
	v_add_f32_e32 v12, 1.0, v12
	v_rcp_f32_e32 v19, v12
	s_nop 0
	v_pk_mul_f32 v[12:13], v[18:19], v[16:17]
	s_nop 0
	v_pk_mul_f32 v[14:15], v[12:13], v[12:13]
	v_and_b32_e32 v18, 0xffff0000, v6
	v_pk_fma_f32 v[14:15], v[4:5], v[4:5], v[14:15]
	v_and_b32_e32 v19, 0xffff0000, v7
	v_add_f32_e32 v14, v14, v20
	v_add_f32_e32 v22, v15, v14
	v_lshlrev_b32_e32 v14, 16, v6
	v_mul_f32_e32 v6, 0x3d372713, v18
	v_lshlrev_b32_e32 v15, 16, v7
	v_mul_f32_e32 v6, v6, v18
	v_mov_b32_e32 v7, v18
	v_fmac_f32_e32 v7, v6, v7
	v_mul_f32_e32 v6, 0x3f4c422a, v7
	v_mul_f32_e32 v6, -2.0, v6
	v_mul_f32_e32 v6, 0x3fb8aa3b, v6
	v_exp_f32_e32 v6, v6
	v_mul_f32_e32 v16, 0x3d372713, v14
	v_mul_f32_e32 v16, v16, v14
	v_mov_b32_e32 v17, v14
	v_add_f32_e32 v6, 1.0, v6
	v_rcp_f32_e32 v20, v6
	v_mul_f32_e32 v6, 0x3d372713, v15
	v_mul_f32_e32 v6, v6, v15
	v_mov_b32_e32 v7, v15
	v_fmac_f32_e32 v17, v16, v17
	v_fmac_f32_e32 v7, v6, v7
	v_mul_f32_e32 v16, 0x3f4c422a, v17
	v_mul_f32_e32 v6, 0x3f4c422a, v7
	v_mul_f32_e32 v16, -2.0, v16
	v_mul_f32_e32 v6, -2.0, v6
	v_mul_f32_e32 v16, 0x3fb8aa3b, v16
	v_mul_f32_e32 v6, 0x3fb8aa3b, v6
	v_exp_f32_e32 v16, v16
	v_exp_f32_e32 v6, v6
	v_add_f32_e32 v16, 1.0, v16
	v_add_f32_e32 v6, 1.0, v6
	v_rcp_f32_e32 v16, v16
	v_rcp_f32_e32 v17, v6
	s_nop 0
	v_pk_mul_f32 v[6:7], v[16:17], v[14:15]
	v_mul_f32_e32 v14, 0x3d372713, v19
	v_mul_f32_e32 v14, v14, v19
	v_mov_b32_e32 v15, v19
	v_fmac_f32_e32 v15, v14, v15
	v_mul_f32_e32 v14, 0x3f4c422a, v15
	v_mul_f32_e32 v14, -2.0, v14
	v_mul_f32_e32 v14, 0x3fb8aa3b, v14
	v_exp_f32_e32 v14, v14
	s_nop 0
	v_add_f32_e32 v14, 1.0, v14
	v_rcp_f32_e32 v21, v14
	s_nop 0
	v_pk_mul_f32 v[14:15], v[20:21], v[18:19]
	s_nop 0
	v_pk_mul_f32 v[16:17], v[14:15], v[14:15]
	s_nop 0
	v_pk_fma_f32 v[16:17], v[6:7], v[6:7], v[16:17]
	s_nop 0
	v_add_f32_e32 v16, v16, v22
	v_add_f32_e32 v22, v17, v16
	v_lshlrev_b32_e32 v16, 16, v0
	v_mul_f32_e32 v18, 0x3d372713, v16
	v_mul_f32_e32 v18, v18, v16
	v_mov_b32_e32 v19, v16
	v_fmac_f32_e32 v19, v18, v19
	v_and_b32_e32 v0, 0xffff0000, v0
	v_mul_f32_e32 v18, 0x3f4c422a, v19
	v_mul_f32_e32 v19, 0x3d372713, v0
	v_mul_f32_e32 v19, v19, v0
	v_mov_b32_e32 v20, v0
	v_fmac_f32_e32 v20, v19, v20
	v_mul_f32_e32 v19, 0x3f4c422a, v20
	v_mul_f32_e32 v19, -2.0, v19
	v_mul_f32_e32 v19, 0x3fb8aa3b, v19
	v_exp_f32_e32 v19, v19
	v_lshlrev_b32_e32 v17, 16, v1
	v_mov_b32_e32 v21, v17
	v_mul_f32_e32 v18, -2.0, v18
	v_add_f32_e32 v19, 1.0, v19
	v_rcp_f32_e32 v20, v19
	v_mul_f32_e32 v19, 0x3d372713, v17
	v_mul_f32_e32 v19, v19, v17
	v_fmac_f32_e32 v21, v19, v21
	v_mul_f32_e32 v19, 0x3f4c422a, v21
	v_mul_f32_e32 v19, -2.0, v19
	v_mul_f32_e32 v18, 0x3fb8aa3b, v18
	v_mul_f32_e32 v19, 0x3fb8aa3b, v19
	v_exp_f32_e32 v18, v18
	v_exp_f32_e32 v19, v19
	v_and_b32_e32 v1, 0xffff0000, v1
	v_add_f32_e32 v18, 1.0, v18
	v_add_f32_e32 v19, 1.0, v19
	v_rcp_f32_e32 v18, v18
	v_rcp_f32_e32 v19, v19
	s_nop 0
	v_pk_mul_f32 v[16:17], v[18:19], v[16:17]
	v_mul_f32_e32 v18, 0x3d372713, v1
	v_mul_f32_e32 v18, v18, v1
	v_mov_b32_e32 v19, v1
	v_fmac_f32_e32 v19, v18, v19
	v_mul_f32_e32 v18, 0x3f4c422a, v19
	v_mul_f32_e32 v18, -2.0, v18
	v_mul_f32_e32 v18, 0x3fb8aa3b, v18
	v_exp_f32_e32 v18, v18
	s_nop 0
	v_add_f32_e32 v18, 1.0, v18
	v_rcp_f32_e32 v21, v18
	s_nop 0
	v_pk_mul_f32 v[18:19], v[20:21], v[0:1]
	s_nop 0
	v_pk_mul_f32 v[0:1], v[18:19], v[18:19]
	s_nop 0
	v_pk_fma_f32 v[0:1], v[16:17], v[16:17], v[0:1]
	s_nop 0
	v_add_f32_e32 v0, v0, v22
	v_add_f32_e32 v92, v1, v0
	v_lshlrev_b32_e32 v0, 16, v2
	v_mul_f32_e32 v20, 0x3d372713, v0
	v_mul_f32_e32 v20, v20, v0
	v_mov_b32_e32 v21, v0
	v_fmac_f32_e32 v21, v20, v21
	v_and_b32_e32 v2, 0xffff0000, v2
	v_mul_f32_e32 v20, 0x3f4c422a, v21
	v_mul_f32_e32 v21, 0x3d372713, v2
	v_mul_f32_e32 v21, v21, v2
	v_mov_b32_e32 v22, v2
	v_fmac_f32_e32 v22, v21, v22
	v_mul_f32_e32 v21, 0x3f4c422a, v22
	v_mul_f32_e32 v21, -2.0, v21
	v_mul_f32_e32 v21, 0x3fb8aa3b, v21
	v_exp_f32_e32 v21, v21
	v_lshlrev_b32_e32 v1, 16, v3
	v_mov_b32_e32 v23, v1
	v_mul_f32_e32 v20, -2.0, v20
	v_add_f32_e32 v21, 1.0, v21
	v_rcp_f32_e32 v22, v21
	v_mul_f32_e32 v21, 0x3d372713, v1
	v_mul_f32_e32 v21, v21, v1
	v_fmac_f32_e32 v23, v21, v23
	v_mul_f32_e32 v21, 0x3f4c422a, v23
	v_mul_f32_e32 v21, -2.0, v21
	v_mul_f32_e32 v20, 0x3fb8aa3b, v20
	v_mul_f32_e32 v21, 0x3fb8aa3b, v21
	v_exp_f32_e32 v20, v20
	v_exp_f32_e32 v21, v21
	v_and_b32_e32 v3, 0xffff0000, v3
	v_add_f32_e32 v20, 1.0, v20
	v_add_f32_e32 v21, 1.0, v21
	v_rcp_f32_e32 v20, v20
	v_rcp_f32_e32 v21, v21
	s_nop 0
	v_pk_mul_f32 v[20:21], v[20:21], v[0:1]
	v_mul_f32_e32 v0, 0x3d372713, v3
	v_mul_f32_e32 v0, v0, v3
	v_mov_b32_e32 v1, v3
	v_fmac_f32_e32 v1, v0, v1
	v_mul_f32_e32 v0, 0x3f4c422a, v1
	v_mul_f32_e32 v0, -2.0, v0
	v_mul_f32_e32 v0, 0x3fb8aa3b, v0
	v_exp_f32_e32 v0, v0
	s_nop 0
	v_add_f32_e32 v0, 1.0, v0
	v_rcp_f32_e32 v23, v0
	s_nop 0
	v_pk_mul_f32 v[22:23], v[22:23], v[2:3]
	s_nop 0
	v_pk_mul_f32 v[0:1], v[22:23], v[22:23]
	s_nop 0
	v_pk_fma_f32 v[0:1], v[20:21], v[20:21], v[0:1]
	s_nop 0
	v_add_f32_e32 v0, v0, v92
	v_add_f32_e32 v0, v1, v0
	v_fmamk_f32 v0, v0, 0x3c800000, v158
	v_cmp_gt_f32_e32 vcc, s82, v0
	v_mul_f32_e32 v1, 0x4b800000, v0
	s_nop 0
	v_cndmask_b32_e32 v0, v0, v1, vcc
	v_rsq_f32_e32 v92, v0
	global_load_dwordx4 v[0:3], v[66:67], off offset:240
	v_mul_f32_e32 v93, 0x45800000, v92
	v_cndmask_b32_e32 v92, v92, v93, vcc
	v_mul_f32_e32 v24, v24, v92
	v_mul_f32_e32 v8, v8, v92
	v_mul_f32_e32 v4, v4, v92
	s_waitcnt vmcnt(1)
	v_mul_f32_e32 v24, v106, v24
	v_cvt_pk_bf16_f32 v24, v24, v157
	ds_write_b16 v68, v24
	v_mul_f32_e32 v24, v25, v92
	v_mul_f32_e32 v24, v107, v24
	v_cvt_pk_bf16_f32 v24, v24, v157
	ds_write_b16 v68, v24 offset:272
	v_mul_f32_e32 v24, v26, v92
	v_mul_f32_e32 v24, v108, v24
	v_cvt_pk_bf16_f32 v24, v24, v157
	ds_write_b16 v68, v24 offset:544
	v_mul_f32_e32 v24, v27, v92
	v_mul_f32_e32 v24, v109, v24
	v_cvt_pk_bf16_f32 v24, v24, v157
	ds_write_b16 v68, v24 offset:816
	v_mul_f32_e32 v24, v28, v92
	v_mul_f32_e32 v24, v102, v24
	v_cvt_pk_bf16_f32 v24, v24, v157
	ds_write_b16 v68, v24 offset:1088
	v_mul_f32_e32 v24, v29, v92
	v_mul_f32_e32 v24, v103, v24
	v_cvt_pk_bf16_f32 v24, v24, v157
	ds_write_b16 v68, v24 offset:1360
	v_mul_f32_e32 v24, v30, v92
	v_mul_f32_e32 v24, v104, v24
	v_cvt_pk_bf16_f32 v24, v24, v157
	ds_write_b16 v68, v24 offset:1632
	v_mul_f32_e32 v24, v31, v92
	v_mul_f32_e32 v24, v105, v24
	v_cvt_pk_bf16_f32 v24, v24, v157
	ds_write_b16 v68, v24 offset:1904
	v_mul_f32_e32 v24, v32, v92
	v_mul_f32_e32 v24, v98, v24
	v_cvt_pk_bf16_f32 v24, v24, v157
	ds_write_b16 v68, v24 offset:2176
	v_mul_f32_e32 v24, v33, v92
	v_mul_f32_e32 v24, v99, v24
	v_cvt_pk_bf16_f32 v24, v24, v157
	ds_write_b16 v68, v24 offset:2448
	v_mul_f32_e32 v24, v34, v92
	v_mul_f32_e32 v24, v100, v24
	v_cvt_pk_bf16_f32 v24, v24, v157
	ds_write_b16 v68, v24 offset:2720
	v_mul_f32_e32 v24, v35, v92
	v_mul_f32_e32 v24, v101, v24
	v_cvt_pk_bf16_f32 v24, v24, v157
	ds_write_b16 v68, v24 offset:2992
	v_mul_f32_e32 v24, v36, v92
	v_mul_f32_e32 v24, v94, v24
	v_cvt_pk_bf16_f32 v24, v24, v157
	ds_write_b16 v68, v24 offset:3264
	v_mul_f32_e32 v24, v37, v92
	v_mul_f32_e32 v24, v95, v24
	v_cvt_pk_bf16_f32 v24, v24, v157
	ds_write_b16 v68, v24 offset:3536
	v_mul_f32_e32 v24, v38, v92
	v_mul_f32_e32 v24, v96, v24
	v_cvt_pk_bf16_f32 v24, v24, v157
	ds_write_b16 v68, v24 offset:3808
	v_mul_f32_e32 v24, v39, v92
	v_mul_f32_e32 v24, v97, v24
	v_cvt_pk_bf16_f32 v24, v24, v157
	ds_write_b16 v68, v24 offset:4080
	v_mul_f32_e32 v24, v40, v92
	s_waitcnt vmcnt(8)
	v_mul_f32_e32 v24, v128, v24
	v_cvt_pk_bf16_f32 v24, v24, v157
	ds_write_b16 v68, v24 offset:4352
	v_mul_f32_e32 v24, v41, v92
	v_mul_f32_e32 v24, v129, v24
	v_cvt_pk_bf16_f32 v24, v24, v157
	ds_write_b16 v68, v24 offset:4624
	v_mul_f32_e32 v24, v42, v92
	v_mul_f32_e32 v24, v130, v24
	v_cvt_pk_bf16_f32 v24, v24, v157
	ds_write_b16 v68, v24 offset:4896
	v_mul_f32_e32 v24, v43, v92
	v_mul_f32_e32 v24, v131, v24
	v_cvt_pk_bf16_f32 v24, v24, v157
	ds_write_b16 v68, v24 offset:5168
	v_mul_f32_e32 v24, v44, v92
	v_mul_f32_e32 v24, v124, v24
	v_cvt_pk_bf16_f32 v24, v24, v157
	ds_write_b16 v68, v24 offset:5440
	v_mul_f32_e32 v24, v45, v92
	v_mul_f32_e32 v24, v125, v24
	v_cvt_pk_bf16_f32 v24, v24, v157
	ds_write_b16 v68, v24 offset:5712
	v_mul_f32_e32 v24, v46, v92
	v_mul_f32_e32 v24, v126, v24
	v_cvt_pk_bf16_f32 v24, v24, v157
	ds_write_b16 v68, v24 offset:5984
	v_mul_f32_e32 v24, v47, v92
	v_mul_f32_e32 v24, v127, v24
	v_cvt_pk_bf16_f32 v24, v24, v157
	ds_write_b16 v68, v24 offset:6256
	v_mul_f32_e32 v24, v48, v92
	v_mul_f32_e32 v24, v120, v24
	v_cvt_pk_bf16_f32 v24, v24, v157
	ds_write_b16 v68, v24 offset:6528
	v_mul_f32_e32 v24, v49, v92
	v_mul_f32_e32 v24, v121, v24
	v_cvt_pk_bf16_f32 v24, v24, v157
	ds_write_b16 v68, v24 offset:6800
	v_mul_f32_e32 v24, v50, v92
	v_mul_f32_e32 v24, v122, v24
	v_cvt_pk_bf16_f32 v24, v24, v157
	ds_write_b16 v68, v24 offset:7072
	v_mul_f32_e32 v24, v51, v92
	v_mul_f32_e32 v24, v123, v24
	v_cvt_pk_bf16_f32 v24, v24, v157
	ds_write_b16 v68, v24 offset:7344
	v_mul_f32_e32 v24, v52, v92
	v_mul_f32_e32 v24, v110, v24
	v_cvt_pk_bf16_f32 v24, v24, v157
	ds_write_b16 v68, v24 offset:7616
	v_mul_f32_e32 v24, v53, v92
	v_mul_f32_e32 v24, v111, v24
	v_cvt_pk_bf16_f32 v24, v24, v157
	ds_write_b16 v68, v24 offset:7888
	v_mul_f32_e32 v24, v54, v92
	v_mul_f32_e32 v24, v112, v24
	v_cvt_pk_bf16_f32 v24, v24, v157
	ds_write_b16 v68, v24 offset:8160
	v_mul_f32_e32 v24, v55, v92
	v_mul_f32_e32 v24, v113, v24
	v_cvt_pk_bf16_f32 v24, v24, v157
	ds_write_b16 v68, v24 offset:8432
	v_mul_f32_e32 v24, v56, v92
	s_waitcnt vmcnt(4)
	v_mul_f32_e32 v24, v144, v24
	v_cvt_pk_bf16_f32 v24, v24, v157
	ds_write_b16 v68, v24 offset:8704
	v_mul_f32_e32 v24, v57, v92
	v_mul_f32_e32 v24, v145, v24
	v_cvt_pk_bf16_f32 v24, v24, v157
	ds_write_b16 v68, v24 offset:8976
	v_mul_f32_e32 v24, v58, v92
	v_mul_f32_e32 v24, v146, v24
	v_cvt_pk_bf16_f32 v24, v24, v157
	ds_write_b16 v68, v24 offset:9248
	v_mul_f32_e32 v24, v59, v92
	v_mul_f32_e32 v24, v147, v24
	v_cvt_pk_bf16_f32 v24, v24, v157
	ds_write_b16 v68, v24 offset:9520
	v_mul_f32_e32 v24, v60, v92
	v_mul_f32_e32 v24, v140, v24
	v_cvt_pk_bf16_f32 v24, v24, v157
	ds_write_b16 v68, v24 offset:9792
	v_mul_f32_e32 v24, v61, v92
	v_mul_f32_e32 v24, v141, v24
	v_cvt_pk_bf16_f32 v24, v24, v157
	ds_write_b16 v68, v24 offset:10064
	v_mul_f32_e32 v24, v62, v92
	v_mul_f32_e32 v24, v142, v24
	v_cvt_pk_bf16_f32 v24, v24, v157
	ds_write_b16 v68, v24 offset:10336
	v_mul_f32_e32 v24, v63, v92
	v_mul_f32_e32 v24, v143, v24
	v_cvt_pk_bf16_f32 v24, v24, v157
	ds_write_b16 v68, v24 offset:10608
	v_mul_f32_e32 v24, v88, v92
	v_mul_f32_e32 v24, v136, v24
	v_cvt_pk_bf16_f32 v24, v24, v157
	ds_write_b16 v68, v24 offset:10880
	v_mul_f32_e32 v24, v89, v92
	v_mul_f32_e32 v24, v137, v24
	v_cvt_pk_bf16_f32 v24, v24, v157
	ds_write_b16 v68, v24 offset:11152
	v_mul_f32_e32 v24, v90, v92
	v_mul_f32_e32 v24, v138, v24
	v_cvt_pk_bf16_f32 v24, v24, v157
	ds_write_b16 v68, v24 offset:11424
	v_mul_f32_e32 v24, v91, v92
	v_mul_f32_e32 v24, v139, v24
	v_mul_f32_e32 v8, v132, v8
	v_cvt_pk_bf16_f32 v24, v24, v157
	ds_write_b16 v68, v24 offset:11696
	v_cvt_pk_bf16_f32 v8, v8, v157
	ds_write_b16 v68, v8 offset:11968
	v_mul_f32_e32 v8, v10, v92
	v_mul_f32_e32 v8, v133, v8
	v_cvt_pk_bf16_f32 v8, v8, v157
	ds_write_b16 v68, v8 offset:12240
	v_mul_f32_e32 v8, v9, v92
	v_mul_f32_e32 v8, v134, v8
	v_cvt_pk_bf16_f32 v8, v8, v157
	ds_write_b16 v68, v8 offset:12512
	v_mul_f32_e32 v8, v11, v92
	v_mul_f32_e32 v8, v135, v8
	s_waitcnt vmcnt(0)
	v_mul_f32_e32 v4, v162, v4
	v_cvt_pk_bf16_f32 v8, v8, v157
	ds_write_b16 v68, v8 offset:12784
	v_cvt_pk_bf16_f32 v4, v4, v157
	ds_write_b16 v68, v4 offset:13056
	v_mul_f32_e32 v4, v12, v92
	v_mul_f32_e32 v4, v163, v4
	v_cvt_pk_bf16_f32 v4, v4, v157
	ds_write_b16 v68, v4 offset:13328
	v_mul_f32_e32 v4, v5, v92
	v_mul_f32_e32 v4, v164, v4
	v_cvt_pk_bf16_f32 v4, v4, v157
	ds_write_b16 v68, v4 offset:13600
	v_mul_f32_e32 v4, v13, v92
	v_mul_f32_e32 v4, v165, v4
	v_cvt_pk_bf16_f32 v4, v4, v157
	ds_write_b16 v68, v4 offset:13872
	v_mul_f32_e32 v4, v6, v92
	v_mul_f32_e32 v4, v152, v4
	v_cvt_pk_bf16_f32 v4, v4, v157
	ds_write_b16 v68, v4 offset:14144
	v_mul_f32_e32 v4, v14, v92
	v_mul_f32_e32 v4, v153, v4
	v_cvt_pk_bf16_f32 v4, v4, v157
	ds_write_b16 v68, v4 offset:14416
	v_mul_f32_e32 v4, v7, v92
	v_mul_f32_e32 v4, v154, v4
	v_cvt_pk_bf16_f32 v4, v4, v157
	ds_write_b16 v68, v4 offset:14688
	v_mul_f32_e32 v4, v15, v92
	v_mul_f32_e32 v4, v155, v4
	v_cvt_pk_bf16_f32 v4, v4, v157
	ds_write_b16 v68, v4 offset:14960
	v_mul_f32_e32 v4, v16, v92
	v_mul_f32_e32 v4, v148, v4
	v_cvt_pk_bf16_f32 v4, v4, v157
	ds_write_b16 v68, v4 offset:15232
	v_mul_f32_e32 v4, v18, v92
	v_mul_f32_e32 v4, v149, v4
	v_cvt_pk_bf16_f32 v4, v4, v157
	ds_write_b16 v68, v4 offset:15504
	v_mul_f32_e32 v4, v17, v92
	v_mul_f32_e32 v4, v150, v4
	v_cvt_pk_bf16_f32 v4, v4, v157
	ds_write_b16 v68, v4 offset:15776
	v_mul_f32_e32 v4, v19, v92
	v_mul_f32_e32 v4, v151, v4
	v_cvt_pk_bf16_f32 v4, v4, v157
	ds_write_b16 v68, v4 offset:16048
	v_mul_f32_e32 v4, v20, v92
	v_mul_f32_e32 v0, v0, v4
	v_cvt_pk_bf16_f32 v0, v0, v157
	ds_write_b16 v68, v0 offset:16320
	v_mul_f32_e32 v0, v22, v92
	v_mul_f32_e32 v0, v1, v0
	v_cvt_pk_bf16_f32 v0, v0, v157
	ds_write_b16 v68, v0 offset:16592
	v_mul_f32_e32 v0, v21, v92
	v_mul_f32_e32 v0, v2, v0
	v_cvt_pk_bf16_f32 v0, v0, v157
	ds_write_b16 v68, v0 offset:16864
	v_mul_f32_e32 v0, v23, v92
	v_mul_f32_e32 v0, v3, v0
	v_cvt_pk_bf16_f32 v0, v0, v157
	ds_write_b16 v69, v0
	s_waitcnt lgkmcnt(0)
	s_barrier
	global_load_dwordx4 v[0:3], v[70:71], off
	global_load_dwordx4 v[4:7], v[72:73], off
	global_load_dwordx4 v[8:11], v[74:75], off
	global_load_dwordx4 v[12:15], v[76:77], off
	global_load_dwordx4 v[16:19], v[70:71], off offset:64
	global_load_dwordx4 v[20:23], v[72:73], off offset:64
	global_load_dwordx4 v[24:27], v[74:75], off offset:64
	global_load_dwordx4 v[28:31], v[76:77], off offset:64
	global_load_dwordx4 v[32:35], v[70:71], off offset:128
	global_load_dwordx4 v[36:39], v[72:73], off offset:128
	global_load_dwordx4 v[40:43], v[74:75], off offset:128
	global_load_dwordx4 v[44:47], v[76:77], off offset:128
	global_load_dwordx4 v[48:51], v[70:71], off offset:192
	global_load_dwordx4 v[88:91], v[72:73], off offset:192
	global_load_dwordx4 v[92:95], v[74:75], off offset:192
	global_load_dwordx4 v[96:99], v[76:77], off offset:192
	ds_read_b128 v[52:55], v119
	ds_read_b128 v[56:59], v119 offset:4352
	ds_read_b128 v[60:63], v119 offset:8704
	ds_read_b128 v[100:103], v119 offset:13056
	s_waitcnt vmcnt(15) lgkmcnt(3)
	v_mfma_f32_16x16x32_bf16 v[104:107], v[52:55], v[0:3], 0
	s_waitcnt lgkmcnt(2)
	v_mfma_f32_16x16x32_bf16 v[108:111], v[56:59], v[0:3], 0
	s_waitcnt lgkmcnt(1)
	v_mfma_f32_16x16x32_bf16 v[112:115], v[60:63], v[0:3], 0
	s_waitcnt lgkmcnt(0)
	v_mfma_f32_16x16x32_bf16 v[0:3], v[100:103], v[0:3], 0
	s_waitcnt vmcnt(14)
	v_mfma_f32_16x16x32_bf16 v[120:123], v[52:55], v[4:7], 0
	v_mfma_f32_16x16x32_bf16 v[124:127], v[56:59], v[4:7], 0
	v_mfma_f32_16x16x32_bf16 v[128:131], v[60:63], v[4:7], 0
	v_mfma_f32_16x16x32_bf16 v[4:7], v[100:103], v[4:7], 0
	s_waitcnt vmcnt(13)
	v_mfma_f32_16x16x32_bf16 v[132:135], v[52:55], v[8:11], 0
	v_mfma_f32_16x16x32_bf16 v[136:139], v[56:59], v[8:11], 0
	v_mfma_f32_16x16x32_bf16 v[140:143], v[60:63], v[8:11], 0
	v_mfma_f32_16x16x32_bf16 v[8:11], v[100:103], v[8:11], 0
	s_waitcnt vmcnt(12)
	v_mfma_f32_16x16x32_bf16 v[52:55], v[52:55], v[12:15], 0
	v_mfma_f32_16x16x32_bf16 v[56:59], v[56:59], v[12:15], 0
	v_mfma_f32_16x16x32_bf16 v[60:63], v[60:63], v[12:15], 0
	v_mfma_f32_16x16x32_bf16 v[12:15], v[100:103], v[12:15], 0
	ds_read_b128 v[100:103], v119 offset:64
	ds_read_b128 v[144:147], v119 offset:4416
	ds_read_b128 v[148:151], v119 offset:8768
	ds_read_b128 v[152:155], v119 offset:13120
	s_waitcnt vmcnt(11) lgkmcnt(3)
	v_mfma_f32_16x16x32_bf16 v[104:107], v[100:103], v[16:19], v[104:107]
	s_waitcnt lgkmcnt(2)
	v_mfma_f32_16x16x32_bf16 v[108:111], v[144:147], v[16:19], v[108:111]
	s_waitcnt lgkmcnt(1)
	v_mfma_f32_16x16x32_bf16 v[112:115], v[148:151], v[16:19], v[112:115]
	s_waitcnt lgkmcnt(0)
	v_mfma_f32_16x16x32_bf16 v[0:3], v[152:155], v[16:19], v[0:3]
	s_waitcnt vmcnt(10)
	v_mfma_f32_16x16x32_bf16 v[16:19], v[100:103], v[20:23], v[120:123]
	v_mfma_f32_16x16x32_bf16 v[120:123], v[144:147], v[20:23], v[124:127]
	v_mfma_f32_16x16x32_bf16 v[124:127], v[148:151], v[20:23], v[128:131]
	v_mfma_f32_16x16x32_bf16 v[4:7], v[152:155], v[20:23], v[4:7]
	s_waitcnt vmcnt(9)
	v_mfma_f32_16x16x32_bf16 v[20:23], v[100:103], v[24:27], v[132:135]
	v_mfma_f32_16x16x32_bf16 v[128:131], v[144:147], v[24:27], v[136:139]
	v_mfma_f32_16x16x32_bf16 v[132:135], v[148:151], v[24:27], v[140:143]
	v_mfma_f32_16x16x32_bf16 v[8:11], v[152:155], v[24:27], v[8:11]
	s_waitcnt vmcnt(8)
	v_mfma_f32_16x16x32_bf16 v[24:27], v[100:103], v[28:31], v[52:55]
	v_mfma_f32_16x16x32_bf16 v[52:55], v[144:147], v[28:31], v[56:59]
	v_mfma_f32_16x16x32_bf16 v[56:59], v[148:151], v[28:31], v[60:63]
	v_mfma_f32_16x16x32_bf16 v[12:15], v[152:155], v[28:31], v[12:15]
	ds_read_b128 v[28:31], v119 offset:128
	s_nop 0
	ds_read_b128 v[60:63], v119 offset:4480
	ds_read_b128 v[100:103], v119 offset:8832
	ds_read_b128 v[136:139], v119 offset:13184
	s_waitcnt vmcnt(7) lgkmcnt(3)
	v_mfma_f32_16x16x32_bf16 v[104:107], v[28:31], v[32:35], v[104:107]
	s_waitcnt lgkmcnt(2)
	v_mfma_f32_16x16x32_bf16 v[108:111], v[60:63], v[32:35], v[108:111]
	s_waitcnt lgkmcnt(1)
	v_mfma_f32_16x16x32_bf16 v[112:115], v[100:103], v[32:35], v[112:115]
	s_waitcnt lgkmcnt(0)
	v_mfma_f32_16x16x32_bf16 v[0:3], v[136:139], v[32:35], v[0:3]
	s_waitcnt vmcnt(6)
	v_mfma_f32_16x16x32_bf16 v[32:35], v[60:63], v[36:39], v[120:123]
	v_mfma_f32_16x16x32_bf16 v[120:123], v[100:103], v[36:39], v[124:127]
	v_mfma_f32_16x16x32_bf16 v[4:7], v[136:139], v[36:39], v[4:7]
	s_waitcnt vmcnt(5)
	v_mfma_f32_16x16x32_bf16 v[124:127], v[60:63], v[40:43], v[128:131]
	v_mfma_f32_16x16x32_bf16 v[8:11], v[136:139], v[40:43], v[8:11]
	s_waitcnt vmcnt(4)
	v_mfma_f32_16x16x32_bf16 v[136:139], v[136:139], v[44:47], v[12:15]
	s_nop 2
	ds_read_b128 v[12:15], v119 offset:192
	ds_read_b128 v[144:147], v119 offset:4544
	ds_read_b128 v[148:151], v119 offset:8896
	ds_read_b128 v[152:155], v119 offset:13248
	v_mfma_f32_16x16x32_bf16 v[16:19], v[28:31], v[36:39], v[16:19]
	v_mfma_f32_16x16x32_bf16 v[20:23], v[28:31], v[40:43], v[20:23]
	v_mfma_f32_16x16x32_bf16 v[128:131], v[100:103], v[40:43], v[132:135]
	v_mfma_f32_16x16x32_bf16 v[132:135], v[28:31], v[44:47], v[24:27]
	s_waitcnt vmcnt(1) lgkmcnt(2)
	v_mfma_f32_16x16x32_bf16 v[24:27], v[144:147], v[92:95], v[124:127]
	s_nop 2
	v_add_u32_e32 v124, s3, v118
	v_mfma_f32_16x16x32_bf16 v[140:143], v[60:63], v[44:47], v[52:55]
	v_ashrrev_i32_e32 v125, 31, v124
	s_add_i32 s3, s3, s6
	s_cmp_lt_i32 s7, s2
	v_mfma_f32_16x16x32_bf16 v[100:103], v[100:103], v[44:47], v[56:59]
	v_mfma_f32_16x16x32_bf16 v[44:47], v[12:15], v[88:91], v[16:19]
	v_mfma_f32_16x16x32_bf16 v[40:43], v[144:147], v[88:91], v[32:35]
	s_waitcnt lgkmcnt(1)
	v_mfma_f32_16x16x32_bf16 v[36:39], v[148:151], v[88:91], v[120:123]
	s_waitcnt lgkmcnt(0)
	v_mfma_f32_16x16x32_bf16 v[32:35], v[152:155], v[88:91], v[4:7]
	v_mad_i64_i32 v[88:89], s[24:25], v124, s9, v[84:85]
	global_load_dword v120, v[78:79], off
	v_mfma_f32_16x16x32_bf16 v[60:63], v[12:15], v[48:51], v[104:107]
	v_mfma_f32_16x16x32_bf16 v[28:31], v[12:15], v[92:95], v[20:23]
	s_nop 1
	v_add_u32_e32 v106, 32, v124
	v_ashrrev_i32_e32 v107, 31, v106
	s_waitcnt vmcnt(0)
	s_nop 1
	v_add_f32_e32 v60, v60, v120
	v_mfma_f32_16x16x32_bf16 v[20:23], v[148:151], v[92:95], v[128:131]
	v_add_f32_e32 v61, v61, v120
	v_add_f32_e32 v62, v62, v120
	v_add_f32_e32 v63, v63, v120
	v_mfma_f32_16x16x32_bf16 v[12:15], v[12:15], v[96:99], v[132:135]
	global_load_dwordx2 v[126:127], v[88:89], off offset:704
	global_load_dwordx2 v[128:129], v[88:89], off offset:736
	global_load_dwordx2 v[130:131], v[88:89], off offset:768
	global_load_dwordx2 v[132:133], v[88:89], off offset:800
	global_load_dword v123, v[80:81], off offset:64
	v_add_u32_e32 v134, 16, v124
	v_mad_i64_i32 v[88:89], s[24:25], v134, s9, v[84:85]
	v_mfma_f32_16x16x32_bf16 v[56:59], v[144:147], v[48:51], v[108:111]
	v_ashrrev_i32_e32 v135, 31, v134
	s_waitcnt vmcnt(0)
	v_add_f32_e32 v44, v44, v123
	v_mfma_f32_16x16x32_bf16 v[52:55], v[148:151], v[48:51], v[112:115]
	s_nop 2
	global_load_dwordx2 v[114:115], v[88:89], off offset:704
	global_load_dwordx2 v[112:113], v[88:89], off offset:736
	global_load_dwordx2 v[110:111], v[88:89], off offset:768
	global_load_dwordx2 v[108:109], v[88:89], off offset:800
	global_load_dword v122, v[80:81], off offset:128
	v_mad_i64_i32 v[88:89], s[24:25], v106, s9, v[84:85]
	v_mfma_f32_16x16x32_bf16 v[48:51], v[152:155], v[48:51], v[0:3]
	v_add_f32_e32 v56, v56, v120
	v_add_f32_e32 v57, v57, v120
	v_add_f32_e32 v58, v58, v120
	v_mfma_f32_16x16x32_bf16 v[0:3], v[152:155], v[96:99], v[136:139]
	v_add_f32_e32 v59, v59, v120
	v_add_f32_e32 v52, v52, v120
	v_add_f32_e32 v53, v53, v120
	v_lshlrev_b32_e32 v136, 16, v126
	v_mul_f32_e32 v137, 0x3d372713, v136
	v_mul_f32_e32 v137, v137, v136
	v_fma_f32 v137, v137, v136, v136
	v_mul_f32_e32 v137, 0x3f4c422a, v137
	v_mul_f32_e32 v137, -2.0, v137
	v_mul_f32_e32 v137, 0x3fb8aa3b, v137
	v_exp_f32_e32 v137, v137
	v_and_b32_e32 v126, 0xffff0000, v126
	v_mfma_f32_16x16x32_bf16 v[16:19], v[152:155], v[92:95], v[8:11]
	v_add_f32_e32 v54, v54, v120
	v_add_f32_e32 v137, 1.0, v137
	v_rcp_f32_e32 v137, v137
	v_mfma_f32_16x16x32_bf16 v[8:11], v[144:147], v[96:99], v[140:143]
	v_add_f32_e32 v55, v55, v120
	v_add_f32_e32 v48, v48, v120
	v_mul_f32_e32 v136, v137, v136
	v_mul_f32_e32 v60, v60, v136
	v_mul_f32_e32 v136, 0x3d372713, v126
	v_mul_f32_e32 v136, v136, v126
	v_fma_f32 v136, v136, v126, v126
	v_mul_f32_e32 v136, 0x3f4c422a, v136
	v_mul_f32_e32 v136, -2.0, v136
	v_mul_f32_e32 v136, 0x3fb8aa3b, v136
	v_exp_f32_e32 v136, v136
	v_mfma_f32_16x16x32_bf16 v[4:7], v[148:151], v[96:99], v[100:103]
	v_add_u32_e32 v96, 48, v124
	global_load_dwordx2 v[104:105], v[88:89], off offset:704
	s_nop 0
	global_load_dwordx2 v[102:103], v[88:89], off offset:736
	global_load_dwordx2 v[100:101], v[88:89], off offset:768
	global_load_dwordx2 v[98:99], v[88:89], off offset:800
	global_load_dword v121, v[80:81], off offset:192
	v_add_f32_e32 v136, 1.0, v136
	v_rcp_f32_e32 v136, v136
	v_mad_i64_i32 v[88:89], s[24:25], v96, s9, v[84:85]
	global_load_dwordx2 v[94:95], v[88:89], off offset:704
	global_load_dwordx2 v[92:93], v[88:89], off offset:736
	global_load_dwordx2 v[90:91], v[88:89], off offset:768
	s_nop 0
	global_load_dwordx2 v[88:89], v[88:89], off offset:800
	v_mul_f32_e32 v126, v136, v126
	v_mul_f32_e32 v61, v61, v126
	v_cvt_pk_bf16_f32 v60, v60, v61
	v_lshlrev_b32_e32 v61, 16, v127
	v_mul_f32_e32 v126, 0x3d372713, v61
	v_mul_f32_e32 v126, v126, v61
	v_fma_f32 v126, v126, v61, v61
	v_mul_f32_e32 v126, 0x3f4c422a, v126
	v_mul_f32_e32 v126, -2.0, v126
	v_mul_f32_e32 v126, 0x3fb8aa3b, v126
	v_exp_f32_e32 v126, v126
	v_lshlrev_b64 v[124:125], 11, v[124:125]
	v_add_f32_e32 v49, v49, v120
	v_add_f32_e32 v50, v50, v120
	v_add_f32_e32 v126, 1.0, v126
	v_rcp_f32_e32 v126, v126
	v_add_f32_e32 v51, v51, v120
	v_add_f32_e32 v45, v45, v123
	v_add_f32_e32 v46, v46, v123
	v_mul_f32_e32 v61, v126, v61
	v_mul_f32_e32 v61, v62, v61
	v_and_b32_e32 v62, 0xffff0000, v127
	v_mul_f32_e32 v126, 0x3d372713, v62
	v_mul_f32_e32 v126, v126, v62
	v_fma_f32 v126, v126, v62, v62
	v_mul_f32_e32 v126, 0x3f4c422a, v126
	v_mul_f32_e32 v126, -2.0, v126
	v_mul_f32_e32 v126, 0x3fb8aa3b, v126
	v_exp_f32_e32 v126, v126
	v_add_f32_e32 v47, v47, v123
	v_add_f32_e32 v40, v40, v123
	v_add_f32_e32 v41, v41, v123
	v_add_f32_e32 v126, 1.0, v126
	v_rcp_f32_e32 v126, v126
	v_add_f32_e32 v42, v42, v123
	v_add_f32_e32 v43, v43, v123
	v_add_f32_e32 v36, v36, v123
	v_mul_f32_e32 v62, v126, v62
	v_mul_f32_e32 v62, v63, v62
	v_cvt_pk_bf16_f32 v61, v61, v62
	v_lshl_add_u64 v[62:63], v[86:87], 0, v[124:125]
	global_store_dwordx2 v[62:63], v[60:61], off offset:1024
	v_lshlrev_b32_e32 v60, 16, v128
	v_mul_f32_e32 v61, 0x3d372713, v60
	v_mul_f32_e32 v61, v61, v60
	v_fma_f32 v61, v61, v60, v60
	v_mul_f32_e32 v61, 0x3f4c422a, v61
	v_mul_f32_e32 v61, -2.0, v61
	v_mul_f32_e32 v61, 0x3fb8aa3b, v61
	v_exp_f32_e32 v61, v61
	v_add_f32_e32 v37, v37, v123
	v_add_f32_e32 v38, v38, v123
	v_add_f32_e32 v39, v39, v123
	v_add_f32_e32 v61, 1.0, v61
	v_rcp_f32_e32 v61, v61
	v_add_f32_e32 v32, v32, v123
	v_add_f32_e32 v33, v33, v123
	v_add_f32_e32 v34, v34, v123
	v_mul_f32_e32 v60, v61, v60
	v_mul_f32_e32 v56, v56, v60
	v_and_b32_e32 v60, 0xffff0000, v128
	v_mul_f32_e32 v61, 0x3d372713, v60
	v_mul_f32_e32 v61, v61, v60
	v_fma_f32 v61, v61, v60, v60
	v_mul_f32_e32 v61, 0x3f4c422a, v61
	v_mul_f32_e32 v61, -2.0, v61
	v_mul_f32_e32 v61, 0x3fb8aa3b, v61
	v_exp_f32_e32 v61, v61
	v_add_f32_e32 v35, v35, v123
	s_waitcnt vmcnt(10)
	v_add_f32_e32 v28, v28, v122
	v_add_f32_e32 v29, v29, v122
	v_add_f32_e32 v61, 1.0, v61
	v_rcp_f32_e32 v61, v61
	v_add_f32_e32 v30, v30, v122
	v_add_f32_e32 v31, v31, v122
	v_add_f32_e32 v24, v24, v122
	v_mul_f32_e32 v60, v61, v60
	v_mul_f32_e32 v57, v57, v60
	v_cvt_pk_bf16_f32 v56, v56, v57
	v_lshlrev_b32_e32 v57, 16, v129
	v_mul_f32_e32 v60, 0x3d372713, v57
	v_mul_f32_e32 v60, v60, v57
	v_fma_f32 v60, v60, v57, v57
	v_mul_f32_e32 v60, 0x3f4c422a, v60
	v_mul_f32_e32 v60, -2.0, v60
	v_mul_f32_e32 v60, 0x3fb8aa3b, v60
	v_exp_f32_e32 v60, v60
	v_add_f32_e32 v25, v25, v122
	v_add_f32_e32 v26, v26, v122
	v_add_f32_e32 v27, v27, v122
	v_add_f32_e32 v60, 1.0, v60
	v_rcp_f32_e32 v60, v60
	v_add_f32_e32 v20, v20, v122
	v_add_f32_e32 v21, v21, v122
	v_add_f32_e32 v22, v22, v122
	v_mul_f32_e32 v57, v60, v57
	v_mul_f32_e32 v57, v58, v57
	v_and_b32_e32 v58, 0xffff0000, v129
	v_mul_f32_e32 v60, 0x3d372713, v58
	v_mul_f32_e32 v60, v60, v58
	v_fma_f32 v60, v60, v58, v58
	v_mul_f32_e32 v60, 0x3f4c422a, v60
	v_mul_f32_e32 v60, -2.0, v60
	v_mul_f32_e32 v60, 0x3fb8aa3b, v60
	v_exp_f32_e32 v60, v60
	v_add_f32_e32 v23, v23, v122
	v_add_f32_e32 v16, v16, v122
	v_add_f32_e32 v17, v17, v122
	v_add_f32_e32 v60, 1.0, v60
	v_rcp_f32_e32 v60, v60
	v_add_f32_e32 v18, v18, v122
	v_add_f32_e32 v19, v19, v122
	s_waitcnt vmcnt(5)
	v_add_f32_e32 v12, v12, v121
	v_mul_f32_e32 v58, v60, v58
	v_mul_f32_e32 v58, v59, v58
	v_cvt_pk_bf16_f32 v57, v57, v58
	global_store_dwordx2 v[62:63], v[56:57], off offset:1056
	v_lshlrev_b32_e32 v56, 16, v130
	v_mul_f32_e32 v57, 0x3d372713, v56
	v_mul_f32_e32 v57, v57, v56
	v_fma_f32 v57, v57, v56, v56
	v_mul_f32_e32 v57, 0x3f4c422a, v57
	v_mul_f32_e32 v57, -2.0, v57
	v_mul_f32_e32 v57, 0x3fb8aa3b, v57
	v_exp_f32_e32 v57, v57
	v_add_f32_e32 v13, v13, v121
	v_add_f32_e32 v14, v14, v121
	v_ashrrev_i32_e32 v97, 31, v96
	v_add_f32_e32 v57, 1.0, v57
	v_rcp_f32_e32 v57, v57
	v_add_f32_e32 v15, v15, v121
	v_add_f32_e32 v8, v8, v121
	v_add_f32_e32 v9, v9, v121
	v_mul_f32_e32 v56, v57, v56
	v_mul_f32_e32 v52, v52, v56
	v_and_b32_e32 v56, 0xffff0000, v130
	v_mul_f32_e32 v57, 0x3d372713, v56
	v_mul_f32_e32 v57, v57, v56
	v_fma_f32 v57, v57, v56, v56
	v_mul_f32_e32 v57, 0x3f4c422a, v57
	v_mul_f32_e32 v57, -2.0, v57
	v_mul_f32_e32 v57, 0x3fb8aa3b, v57
	v_exp_f32_e32 v57, v57
	v_add_f32_e32 v10, v10, v121
	v_add_f32_e32 v11, v11, v121
	v_add_f32_e32 v4, v4, v121
	v_add_f32_e32 v57, 1.0, v57
	v_rcp_f32_e32 v57, v57
	v_add_f32_e32 v5, v5, v121
	v_add_f32_e32 v6, v6, v121
	v_add_f32_e32 v7, v7, v121
	v_mul_f32_e32 v56, v57, v56
	v_mul_f32_e32 v53, v53, v56
	v_cvt_pk_bf16_f32 v52, v52, v53
	v_lshlrev_b32_e32 v53, 16, v131
	v_mul_f32_e32 v56, 0x3d372713, v53
	v_mul_f32_e32 v56, v56, v53
	v_fma_f32 v56, v56, v53, v53
	v_mul_f32_e32 v56, 0x3f4c422a, v56
	v_mul_f32_e32 v56, -2.0, v56
	v_mul_f32_e32 v56, 0x3fb8aa3b, v56
	v_exp_f32_e32 v56, v56
	v_add_f32_e32 v0, v0, v121
	v_add_f32_e32 v1, v1, v121
	v_add_f32_e32 v2, v2, v121
	v_add_f32_e32 v56, 1.0, v56
	v_rcp_f32_e32 v56, v56
	v_add_f32_e32 v3, v3, v121
	v_mul_f32_e32 v53, v56, v53
	v_mul_f32_e32 v53, v54, v53
	v_and_b32_e32 v54, 0xffff0000, v131
	v_mul_f32_e32 v56, 0x3d372713, v54
	v_mul_f32_e32 v56, v56, v54
	v_fma_f32 v56, v56, v54, v54
	v_mul_f32_e32 v56, 0x3f4c422a, v56
	v_mul_f32_e32 v56, -2.0, v56
	v_mul_f32_e32 v56, 0x3fb8aa3b, v56
	v_exp_f32_e32 v56, v56
	s_nop 0
	v_add_f32_e32 v56, 1.0, v56
	v_rcp_f32_e32 v56, v56
	s_nop 0
	v_mul_f32_e32 v54, v56, v54
	v_mul_f32_e32 v54, v55, v54
	v_cvt_pk_bf16_f32 v53, v53, v54
	global_store_dwordx2 v[62:63], v[52:53], off offset:1088
	v_lshlrev_b32_e32 v52, 16, v132
	v_mul_f32_e32 v53, 0x3d372713, v52
	v_mul_f32_e32 v53, v53, v52
	v_fma_f32 v53, v53, v52, v52
	v_mul_f32_e32 v53, 0x3f4c422a, v53
	v_mul_f32_e32 v53, -2.0, v53
	v_mul_f32_e32 v53, 0x3fb8aa3b, v53
	v_exp_f32_e32 v53, v53
	s_nop 0
	v_add_f32_e32 v53, 1.0, v53
	v_rcp_f32_e32 v53, v53
	s_nop 0
	v_mul_f32_e32 v52, v53, v52
	v_mul_f32_e32 v48, v48, v52
	v_and_b32_e32 v52, 0xffff0000, v132
	v_mul_f32_e32 v53, 0x3d372713, v52
	v_mul_f32_e32 v53, v53, v52
	v_fma_f32 v53, v53, v52, v52
	v_mul_f32_e32 v53, 0x3f4c422a, v53
	v_mul_f32_e32 v53, -2.0, v53
	v_mul_f32_e32 v53, 0x3fb8aa3b, v53
	v_exp_f32_e32 v53, v53
	s_nop 0
	v_add_f32_e32 v53, 1.0, v53
	v_rcp_f32_e32 v53, v53
	s_nop 0
	v_mul_f32_e32 v52, v53, v52
	v_mul_f32_e32 v49, v49, v52
	v_cvt_pk_bf16_f32 v48, v48, v49
	v_lshlrev_b32_e32 v49, 16, v133
	v_mul_f32_e32 v52, 0x3d372713, v49
	v_mul_f32_e32 v52, v52, v49
	v_fma_f32 v52, v52, v49, v49
	v_mul_f32_e32 v52, 0x3f4c422a, v52
	v_mul_f32_e32 v52, -2.0, v52
	v_mul_f32_e32 v52, 0x3fb8aa3b, v52
	v_exp_f32_e32 v52, v52
	s_nop 0
	v_add_f32_e32 v52, 1.0, v52
	v_rcp_f32_e32 v52, v52
	s_nop 0
	v_mul_f32_e32 v49, v52, v49
	v_mul_f32_e32 v49, v50, v49
	v_and_b32_e32 v50, 0xffff0000, v133
	v_mul_f32_e32 v52, 0x3d372713, v50
	v_mul_f32_e32 v52, v52, v50
	v_fma_f32 v52, v52, v50, v50
	v_mul_f32_e32 v52, 0x3f4c422a, v52
	v_mul_f32_e32 v52, -2.0, v52
	v_mul_f32_e32 v52, 0x3fb8aa3b, v52
	v_exp_f32_e32 v52, v52
	s_nop 0
	v_add_f32_e32 v52, 1.0, v52
	v_rcp_f32_e32 v52, v52
	s_nop 0
	v_mul_f32_e32 v50, v52, v50
	v_mul_f32_e32 v50, v51, v50
	v_cvt_pk_bf16_f32 v49, v49, v50
	v_lshlrev_b32_e32 v50, 16, v114
	v_mul_f32_e32 v51, 0x3d372713, v50
	v_mul_f32_e32 v51, v51, v50
	v_fma_f32 v51, v51, v50, v50
	v_mul_f32_e32 v51, 0x3f4c422a, v51
	v_mul_f32_e32 v51, -2.0, v51
	v_mul_f32_e32 v51, 0x3fb8aa3b, v51
	v_exp_f32_e32 v51, v51
	global_store_dwordx2 v[62:63], v[48:49], off offset:1120
	v_lshlrev_b64 v[48:49], 11, v[134:135]
	v_add_f32_e32 v51, 1.0, v51
	v_rcp_f32_e32 v51, v51
	s_nop 0
	v_mul_f32_e32 v50, v51, v50
	v_mul_f32_e32 v44, v44, v50
	v_and_b32_e32 v50, 0xffff0000, v114
	v_mul_f32_e32 v51, 0x3d372713, v50
	v_mul_f32_e32 v51, v51, v50
	v_fma_f32 v51, v51, v50, v50
	v_mul_f32_e32 v51, 0x3f4c422a, v51
	v_mul_f32_e32 v51, -2.0, v51
	v_mul_f32_e32 v51, 0x3fb8aa3b, v51
	v_exp_f32_e32 v51, v51
	s_nop 0
	v_add_f32_e32 v51, 1.0, v51
	v_rcp_f32_e32 v51, v51
	s_nop 0
	v_mul_f32_e32 v50, v51, v50
	v_mul_f32_e32 v45, v45, v50
	v_cvt_pk_bf16_f32 v44, v44, v45
	v_lshlrev_b32_e32 v45, 16, v115
	v_mul_f32_e32 v50, 0x3d372713, v45
	v_mul_f32_e32 v50, v50, v45
	v_fma_f32 v50, v50, v45, v45
	v_mul_f32_e32 v50, 0x3f4c422a, v50
	v_mul_f32_e32 v50, -2.0, v50
	v_mul_f32_e32 v50, 0x3fb8aa3b, v50
	v_exp_f32_e32 v50, v50
	s_nop 0
	v_add_f32_e32 v50, 1.0, v50
	v_rcp_f32_e32 v50, v50
	s_nop 0
	v_mul_f32_e32 v45, v50, v45
	v_mul_f32_e32 v45, v46, v45
	v_and_b32_e32 v46, 0xffff0000, v115
	v_mul_f32_e32 v50, 0x3d372713, v46
	v_mul_f32_e32 v50, v50, v46
	v_fma_f32 v50, v50, v46, v46
	v_mul_f32_e32 v50, 0x3f4c422a, v50
	v_mul_f32_e32 v50, -2.0, v50
	v_mul_f32_e32 v50, 0x3fb8aa3b, v50
	v_exp_f32_e32 v50, v50
	s_nop 0
	v_add_f32_e32 v50, 1.0, v50
	v_rcp_f32_e32 v50, v50
	s_nop 0
	v_mul_f32_e32 v46, v50, v46
	v_mul_f32_e32 v46, v47, v46
	v_cvt_pk_bf16_f32 v45, v45, v46
	v_lshl_add_u64 v[46:47], v[86:87], 0, v[48:49]
	global_store_dwordx2 v[46:47], v[44:45], off offset:1024
	v_lshlrev_b32_e32 v44, 16, v112
	v_mul_f32_e32 v45, 0x3d372713, v44
	v_mul_f32_e32 v45, v45, v44
	v_fma_f32 v45, v45, v44, v44
	v_mul_f32_e32 v45, 0x3f4c422a, v45
	v_mul_f32_e32 v45, -2.0, v45
	v_mul_f32_e32 v45, 0x3fb8aa3b, v45
	v_exp_f32_e32 v45, v45
	s_nop 0
	v_add_f32_e32 v45, 1.0, v45
	v_rcp_f32_e32 v45, v45
	s_nop 0
	v_mul_f32_e32 v44, v45, v44
	v_mul_f32_e32 v40, v40, v44
	v_and_b32_e32 v44, 0xffff0000, v112
	v_mul_f32_e32 v45, 0x3d372713, v44
	v_mul_f32_e32 v45, v45, v44
	v_fma_f32 v45, v45, v44, v44
	v_mul_f32_e32 v45, 0x3f4c422a, v45
	v_mul_f32_e32 v45, -2.0, v45
	v_mul_f32_e32 v45, 0x3fb8aa3b, v45
	v_exp_f32_e32 v45, v45
	s_nop 0
	v_add_f32_e32 v45, 1.0, v45
	v_rcp_f32_e32 v45, v45
	s_nop 0
	v_mul_f32_e32 v44, v45, v44
	v_mul_f32_e32 v41, v41, v44
	v_cvt_pk_bf16_f32 v40, v40, v41
	v_lshlrev_b32_e32 v41, 16, v113
	v_mul_f32_e32 v44, 0x3d372713, v41
	v_mul_f32_e32 v44, v44, v41
	v_fma_f32 v44, v44, v41, v41
	v_mul_f32_e32 v44, 0x3f4c422a, v44
	v_mul_f32_e32 v44, -2.0, v44
	v_mul_f32_e32 v44, 0x3fb8aa3b, v44
	v_exp_f32_e32 v44, v44
	s_nop 0
	v_add_f32_e32 v44, 1.0, v44
	v_rcp_f32_e32 v44, v44
	s_nop 0
	v_mul_f32_e32 v41, v44, v41
	v_mul_f32_e32 v41, v42, v41
	v_and_b32_e32 v42, 0xffff0000, v113
	v_mul_f32_e32 v44, 0x3d372713, v42
	v_mul_f32_e32 v44, v44, v42
	v_fma_f32 v44, v44, v42, v42
	v_mul_f32_e32 v44, 0x3f4c422a, v44
	v_mul_f32_e32 v44, -2.0, v44
	v_mul_f32_e32 v44, 0x3fb8aa3b, v44
	v_exp_f32_e32 v44, v44
	s_nop 0
	v_add_f32_e32 v44, 1.0, v44
	v_rcp_f32_e32 v44, v44
	s_nop 0
	v_mul_f32_e32 v42, v44, v42
	v_mul_f32_e32 v42, v43, v42
	v_cvt_pk_bf16_f32 v41, v41, v42
	global_store_dwordx2 v[46:47], v[40:41], off offset:1056
	v_lshlrev_b32_e32 v40, 16, v110
	v_mul_f32_e32 v41, 0x3d372713, v40
	v_mul_f32_e32 v41, v41, v40
	v_fma_f32 v41, v41, v40, v40
	v_mul_f32_e32 v41, 0x3f4c422a, v41
	v_mul_f32_e32 v41, -2.0, v41
	v_mul_f32_e32 v41, 0x3fb8aa3b, v41
	v_exp_f32_e32 v41, v41
	s_nop 0
	v_add_f32_e32 v41, 1.0, v41
	v_rcp_f32_e32 v41, v41
	s_nop 0
	v_mul_f32_e32 v40, v41, v40
	v_mul_f32_e32 v36, v36, v40
	v_and_b32_e32 v40, 0xffff0000, v110
	v_mul_f32_e32 v41, 0x3d372713, v40
	v_mul_f32_e32 v41, v41, v40
	v_fma_f32 v41, v41, v40, v40
	v_mul_f32_e32 v41, 0x3f4c422a, v41
	v_mul_f32_e32 v41, -2.0, v41
	v_mul_f32_e32 v41, 0x3fb8aa3b, v41
	v_exp_f32_e32 v41, v41
	s_nop 0
	v_add_f32_e32 v41, 1.0, v41
	v_rcp_f32_e32 v41, v41
	s_nop 0
	v_mul_f32_e32 v40, v41, v40
	v_mul_f32_e32 v37, v37, v40
	v_cvt_pk_bf16_f32 v36, v36, v37
	v_lshlrev_b32_e32 v37, 16, v111
	v_mul_f32_e32 v40, 0x3d372713, v37
	v_mul_f32_e32 v40, v40, v37
	v_fma_f32 v40, v40, v37, v37
	v_mul_f32_e32 v40, 0x3f4c422a, v40
	v_mul_f32_e32 v40, -2.0, v40
	v_mul_f32_e32 v40, 0x3fb8aa3b, v40
	v_exp_f32_e32 v40, v40
	s_nop 0
	v_add_f32_e32 v40, 1.0, v40
	v_rcp_f32_e32 v40, v40
	s_nop 0
	v_mul_f32_e32 v37, v40, v37
	v_mul_f32_e32 v37, v38, v37
	v_and_b32_e32 v38, 0xffff0000, v111
	v_mul_f32_e32 v40, 0x3d372713, v38
	v_mul_f32_e32 v40, v40, v38
	v_fma_f32 v40, v40, v38, v38
	v_mul_f32_e32 v40, 0x3f4c422a, v40
	v_mul_f32_e32 v40, -2.0, v40
	v_mul_f32_e32 v40, 0x3fb8aa3b, v40
	v_exp_f32_e32 v40, v40
	s_nop 0
	v_add_f32_e32 v40, 1.0, v40
	v_rcp_f32_e32 v40, v40
	s_nop 0
	v_mul_f32_e32 v38, v40, v38
	v_mul_f32_e32 v38, v39, v38
	v_cvt_pk_bf16_f32 v37, v37, v38
	global_store_dwordx2 v[46:47], v[36:37], off offset:1088
	v_lshlrev_b32_e32 v36, 16, v108
	v_mul_f32_e32 v37, 0x3d372713, v36
	v_mul_f32_e32 v37, v37, v36
	v_fma_f32 v37, v37, v36, v36
	v_mul_f32_e32 v37, 0x3f4c422a, v37
	v_mul_f32_e32 v37, -2.0, v37
	v_mul_f32_e32 v37, 0x3fb8aa3b, v37
	v_exp_f32_e32 v37, v37
	s_nop 0
	v_add_f32_e32 v37, 1.0, v37
	v_rcp_f32_e32 v37, v37
	s_nop 0
	v_mul_f32_e32 v36, v37, v36
	v_mul_f32_e32 v32, v32, v36
	v_and_b32_e32 v36, 0xffff0000, v108
	v_mul_f32_e32 v37, 0x3d372713, v36
	v_mul_f32_e32 v37, v37, v36
	v_fma_f32 v37, v37, v36, v36
	v_mul_f32_e32 v37, 0x3f4c422a, v37
	v_mul_f32_e32 v37, -2.0, v37
	v_mul_f32_e32 v37, 0x3fb8aa3b, v37
	v_exp_f32_e32 v37, v37
	s_nop 0
	v_add_f32_e32 v37, 1.0, v37
	v_rcp_f32_e32 v37, v37
	s_nop 0
	v_mul_f32_e32 v36, v37, v36
	v_mul_f32_e32 v33, v33, v36
	v_cvt_pk_bf16_f32 v32, v32, v33
	v_lshlrev_b32_e32 v33, 16, v109
	v_mul_f32_e32 v36, 0x3d372713, v33
	v_mul_f32_e32 v36, v36, v33
	v_fma_f32 v36, v36, v33, v33
	v_mul_f32_e32 v36, 0x3f4c422a, v36
	v_mul_f32_e32 v36, -2.0, v36
	v_mul_f32_e32 v36, 0x3fb8aa3b, v36
	v_exp_f32_e32 v36, v36
	s_nop 0
	v_add_f32_e32 v36, 1.0, v36
	v_rcp_f32_e32 v36, v36
	s_nop 0
	v_mul_f32_e32 v33, v36, v33
	v_mul_f32_e32 v33, v34, v33
	v_and_b32_e32 v34, 0xffff0000, v109
	v_mul_f32_e32 v36, 0x3d372713, v34
	v_mul_f32_e32 v36, v36, v34
	v_fma_f32 v36, v36, v34, v34
	v_mul_f32_e32 v36, 0x3f4c422a, v36
	v_mul_f32_e32 v36, -2.0, v36
	v_mul_f32_e32 v36, 0x3fb8aa3b, v36
	v_exp_f32_e32 v36, v36
	s_nop 0
	v_add_f32_e32 v36, 1.0, v36
	v_rcp_f32_e32 v36, v36
	s_nop 0
	v_mul_f32_e32 v34, v36, v34
	v_mul_f32_e32 v34, v35, v34
	v_cvt_pk_bf16_f32 v33, v33, v34
	v_lshlrev_b32_e32 v34, 16, v104
	v_mul_f32_e32 v35, 0x3d372713, v34
	v_mul_f32_e32 v35, v35, v34
	v_fma_f32 v35, v35, v34, v34
	v_mul_f32_e32 v35, 0x3f4c422a, v35
	v_mul_f32_e32 v35, -2.0, v35
	v_mul_f32_e32 v35, 0x3fb8aa3b, v35
	v_exp_f32_e32 v35, v35
	global_store_dwordx2 v[46:47], v[32:33], off offset:1120
	v_lshlrev_b64 v[32:33], 11, v[106:107]
	v_add_f32_e32 v35, 1.0, v35
	v_rcp_f32_e32 v35, v35
	s_nop 0
	v_mul_f32_e32 v34, v35, v34
	v_mul_f32_e32 v28, v28, v34
	v_and_b32_e32 v34, 0xffff0000, v104
	v_mul_f32_e32 v35, 0x3d372713, v34
	v_mul_f32_e32 v35, v35, v34
	v_fma_f32 v35, v35, v34, v34
	v_mul_f32_e32 v35, 0x3f4c422a, v35
	v_mul_f32_e32 v35, -2.0, v35
	v_mul_f32_e32 v35, 0x3fb8aa3b, v35
	v_exp_f32_e32 v35, v35
	s_nop 0
	v_add_f32_e32 v35, 1.0, v35
	v_rcp_f32_e32 v35, v35
	s_nop 0
	v_mul_f32_e32 v34, v35, v34
	v_mul_f32_e32 v29, v29, v34
	v_cvt_pk_bf16_f32 v28, v28, v29
	v_lshlrev_b32_e32 v29, 16, v105
	v_mul_f32_e32 v34, 0x3d372713, v29
	v_mul_f32_e32 v34, v34, v29
	v_fma_f32 v34, v34, v29, v29
	v_mul_f32_e32 v34, 0x3f4c422a, v34
	v_mul_f32_e32 v34, -2.0, v34
	v_mul_f32_e32 v34, 0x3fb8aa3b, v34
	v_exp_f32_e32 v34, v34
	s_nop 0
	v_add_f32_e32 v34, 1.0, v34
	v_rcp_f32_e32 v34, v34
	s_nop 0
	v_mul_f32_e32 v29, v34, v29
	v_mul_f32_e32 v29, v30, v29
	v_and_b32_e32 v30, 0xffff0000, v105
	v_mul_f32_e32 v34, 0x3d372713, v30
	v_mul_f32_e32 v34, v34, v30
	v_fma_f32 v34, v34, v30, v30
	v_mul_f32_e32 v34, 0x3f4c422a, v34
	v_mul_f32_e32 v34, -2.0, v34
	v_mul_f32_e32 v34, 0x3fb8aa3b, v34
	v_exp_f32_e32 v34, v34
	s_nop 0
	v_add_f32_e32 v34, 1.0, v34
	v_rcp_f32_e32 v34, v34
	s_nop 0
	v_mul_f32_e32 v30, v34, v30
	v_mul_f32_e32 v30, v31, v30
	v_cvt_pk_bf16_f32 v29, v29, v30
	v_lshl_add_u64 v[30:31], v[86:87], 0, v[32:33]
	global_store_dwordx2 v[30:31], v[28:29], off offset:1024
	v_lshlrev_b32_e32 v28, 16, v102
	v_mul_f32_e32 v29, 0x3d372713, v28
	v_mul_f32_e32 v29, v29, v28
	v_fma_f32 v29, v29, v28, v28
	v_mul_f32_e32 v29, 0x3f4c422a, v29
	v_mul_f32_e32 v29, -2.0, v29
	v_mul_f32_e32 v29, 0x3fb8aa3b, v29
	v_exp_f32_e32 v29, v29
	s_nop 0
	v_add_f32_e32 v29, 1.0, v29
	v_rcp_f32_e32 v29, v29
	s_nop 0
	v_mul_f32_e32 v28, v29, v28
	v_mul_f32_e32 v24, v24, v28
	v_and_b32_e32 v28, 0xffff0000, v102
	v_mul_f32_e32 v29, 0x3d372713, v28
	v_mul_f32_e32 v29, v29, v28
	v_fma_f32 v29, v29, v28, v28
	v_mul_f32_e32 v29, 0x3f4c422a, v29
	v_mul_f32_e32 v29, -2.0, v29
	v_mul_f32_e32 v29, 0x3fb8aa3b, v29
	v_exp_f32_e32 v29, v29
	s_nop 0
	v_add_f32_e32 v29, 1.0, v29
	v_rcp_f32_e32 v29, v29
	s_nop 0
	v_mul_f32_e32 v28, v29, v28
	v_mul_f32_e32 v25, v25, v28
	v_cvt_pk_bf16_f32 v24, v24, v25
	v_lshlrev_b32_e32 v25, 16, v103
	v_mul_f32_e32 v28, 0x3d372713, v25
	v_mul_f32_e32 v28, v28, v25
	v_fma_f32 v28, v28, v25, v25
	v_mul_f32_e32 v28, 0x3f4c422a, v28
	v_mul_f32_e32 v28, -2.0, v28
	v_mul_f32_e32 v28, 0x3fb8aa3b, v28
	v_exp_f32_e32 v28, v28
	s_nop 0
	v_add_f32_e32 v28, 1.0, v28
	v_rcp_f32_e32 v28, v28
	s_nop 0
	v_mul_f32_e32 v25, v28, v25
	v_mul_f32_e32 v25, v26, v25
	v_and_b32_e32 v26, 0xffff0000, v103
	v_mul_f32_e32 v28, 0x3d372713, v26
	v_mul_f32_e32 v28, v28, v26
	v_fma_f32 v28, v28, v26, v26
	v_mul_f32_e32 v28, 0x3f4c422a, v28
	v_mul_f32_e32 v28, -2.0, v28
	v_mul_f32_e32 v28, 0x3fb8aa3b, v28
	v_exp_f32_e32 v28, v28
	s_nop 0
	v_add_f32_e32 v28, 1.0, v28
	v_rcp_f32_e32 v28, v28
	s_nop 0
	v_mul_f32_e32 v26, v28, v26
	v_mul_f32_e32 v26, v27, v26
	v_cvt_pk_bf16_f32 v25, v25, v26
	global_store_dwordx2 v[30:31], v[24:25], off offset:1056
	v_lshlrev_b32_e32 v24, 16, v100
	v_mul_f32_e32 v25, 0x3d372713, v24
	v_mul_f32_e32 v25, v25, v24
	v_fma_f32 v25, v25, v24, v24
	v_mul_f32_e32 v25, 0x3f4c422a, v25
	v_mul_f32_e32 v25, -2.0, v25
	v_mul_f32_e32 v25, 0x3fb8aa3b, v25
	v_exp_f32_e32 v25, v25
	s_nop 0
	v_add_f32_e32 v25, 1.0, v25
	v_rcp_f32_e32 v25, v25
	s_nop 0
	v_mul_f32_e32 v24, v25, v24
	v_mul_f32_e32 v20, v20, v24
	v_and_b32_e32 v24, 0xffff0000, v100
	v_mul_f32_e32 v25, 0x3d372713, v24
	v_mul_f32_e32 v25, v25, v24
	v_fma_f32 v25, v25, v24, v24
	v_mul_f32_e32 v25, 0x3f4c422a, v25
	v_mul_f32_e32 v25, -2.0, v25
	v_mul_f32_e32 v25, 0x3fb8aa3b, v25
	v_exp_f32_e32 v25, v25
	s_nop 0
	v_add_f32_e32 v25, 1.0, v25
	v_rcp_f32_e32 v25, v25
	s_nop 0
	v_mul_f32_e32 v24, v25, v24
	v_mul_f32_e32 v21, v21, v24
	v_cvt_pk_bf16_f32 v20, v20, v21
	v_lshlrev_b32_e32 v21, 16, v101
	v_mul_f32_e32 v24, 0x3d372713, v21
	v_mul_f32_e32 v24, v24, v21
	v_fma_f32 v24, v24, v21, v21
	v_mul_f32_e32 v24, 0x3f4c422a, v24
	v_mul_f32_e32 v24, -2.0, v24
	v_mul_f32_e32 v24, 0x3fb8aa3b, v24
	v_exp_f32_e32 v24, v24
	s_nop 0
	v_add_f32_e32 v24, 1.0, v24
	v_rcp_f32_e32 v24, v24
	s_nop 0
	v_mul_f32_e32 v21, v24, v21
	v_mul_f32_e32 v21, v22, v21
	v_and_b32_e32 v22, 0xffff0000, v101
	v_mul_f32_e32 v24, 0x3d372713, v22
	v_mul_f32_e32 v24, v24, v22
	v_fma_f32 v24, v24, v22, v22
	v_mul_f32_e32 v24, 0x3f4c422a, v24
	v_mul_f32_e32 v24, -2.0, v24
	v_mul_f32_e32 v24, 0x3fb8aa3b, v24
	v_exp_f32_e32 v24, v24
	s_nop 0
	v_add_f32_e32 v24, 1.0, v24
	v_rcp_f32_e32 v24, v24
	s_nop 0
	v_mul_f32_e32 v22, v24, v22
	v_mul_f32_e32 v22, v23, v22
	v_cvt_pk_bf16_f32 v21, v21, v22
	global_store_dwordx2 v[30:31], v[20:21], off offset:1088
	v_lshlrev_b32_e32 v20, 16, v98
	v_mul_f32_e32 v21, 0x3d372713, v20
	v_mul_f32_e32 v21, v21, v20
	v_fma_f32 v21, v21, v20, v20
	v_mul_f32_e32 v21, 0x3f4c422a, v21
	v_mul_f32_e32 v21, -2.0, v21
	v_mul_f32_e32 v21, 0x3fb8aa3b, v21
	v_exp_f32_e32 v21, v21
	s_nop 0
	v_add_f32_e32 v21, 1.0, v21
	v_rcp_f32_e32 v21, v21
	s_nop 0
	v_mul_f32_e32 v20, v21, v20
	v_mul_f32_e32 v16, v16, v20
	v_and_b32_e32 v20, 0xffff0000, v98
	v_mul_f32_e32 v21, 0x3d372713, v20
	v_mul_f32_e32 v21, v21, v20
	v_fma_f32 v21, v21, v20, v20
	v_mul_f32_e32 v21, 0x3f4c422a, v21
	v_mul_f32_e32 v21, -2.0, v21
	v_mul_f32_e32 v21, 0x3fb8aa3b, v21
	v_exp_f32_e32 v21, v21
	s_nop 0
	v_add_f32_e32 v21, 1.0, v21
	v_rcp_f32_e32 v21, v21
	s_nop 0
	v_mul_f32_e32 v20, v21, v20
	v_mul_f32_e32 v17, v17, v20
	v_cvt_pk_bf16_f32 v16, v16, v17
	v_lshlrev_b32_e32 v17, 16, v99
	v_mul_f32_e32 v20, 0x3d372713, v17
	v_mul_f32_e32 v20, v20, v17
	v_fma_f32 v20, v20, v17, v17
	v_mul_f32_e32 v20, 0x3f4c422a, v20
	v_mul_f32_e32 v20, -2.0, v20
	v_mul_f32_e32 v20, 0x3fb8aa3b, v20
	v_exp_f32_e32 v20, v20
	s_nop 0
	v_add_f32_e32 v20, 1.0, v20
	v_rcp_f32_e32 v20, v20
	s_nop 0
	v_mul_f32_e32 v17, v20, v17
	v_mul_f32_e32 v17, v18, v17
	v_and_b32_e32 v18, 0xffff0000, v99
	v_mul_f32_e32 v20, 0x3d372713, v18
	v_mul_f32_e32 v20, v20, v18
	v_fma_f32 v20, v20, v18, v18
	v_mul_f32_e32 v20, 0x3f4c422a, v20
	v_mul_f32_e32 v20, -2.0, v20
	v_mul_f32_e32 v20, 0x3fb8aa3b, v20
	v_exp_f32_e32 v20, v20
	s_nop 0
	v_add_f32_e32 v20, 1.0, v20
	v_rcp_f32_e32 v20, v20
	s_nop 0
	v_mul_f32_e32 v18, v20, v18
	v_mul_f32_e32 v18, v19, v18
	v_cvt_pk_bf16_f32 v17, v17, v18
	s_waitcnt vmcnt(14)
	v_lshlrev_b32_e32 v18, 16, v94
	v_mul_f32_e32 v19, 0x3d372713, v18
	v_mul_f32_e32 v19, v19, v18
	v_fma_f32 v19, v19, v18, v18
	v_mul_f32_e32 v19, 0x3f4c422a, v19
	v_mul_f32_e32 v19, -2.0, v19
	v_mul_f32_e32 v19, 0x3fb8aa3b, v19
	v_exp_f32_e32 v19, v19
	global_store_dwordx2 v[30:31], v[16:17], off offset:1120
	v_lshlrev_b64 v[16:17], 11, v[96:97]
	v_add_f32_e32 v19, 1.0, v19
	v_rcp_f32_e32 v19, v19
	s_nop 0
	v_mul_f32_e32 v18, v19, v18
	v_mul_f32_e32 v12, v12, v18
	v_and_b32_e32 v18, 0xffff0000, v94
	v_mul_f32_e32 v19, 0x3d372713, v18
	v_mul_f32_e32 v19, v19, v18
	v_fma_f32 v19, v19, v18, v18
	v_mul_f32_e32 v19, 0x3f4c422a, v19
	v_mul_f32_e32 v19, -2.0, v19
	v_mul_f32_e32 v19, 0x3fb8aa3b, v19
	v_exp_f32_e32 v19, v19
	s_nop 0
	v_add_f32_e32 v19, 1.0, v19
	v_rcp_f32_e32 v19, v19
	s_nop 0
	v_mul_f32_e32 v18, v19, v18
	v_mul_f32_e32 v13, v13, v18
	v_cvt_pk_bf16_f32 v12, v12, v13
	v_lshlrev_b32_e32 v13, 16, v95
	v_mul_f32_e32 v18, 0x3d372713, v13
	v_mul_f32_e32 v18, v18, v13
	v_fma_f32 v18, v18, v13, v13
	v_mul_f32_e32 v18, 0x3f4c422a, v18
	v_mul_f32_e32 v18, -2.0, v18
	v_mul_f32_e32 v18, 0x3fb8aa3b, v18
	v_exp_f32_e32 v18, v18
	s_nop 0
	v_add_f32_e32 v18, 1.0, v18
	v_rcp_f32_e32 v18, v18
	s_nop 0
	v_mul_f32_e32 v13, v18, v13
	v_mul_f32_e32 v13, v14, v13
	v_and_b32_e32 v14, 0xffff0000, v95
	v_mul_f32_e32 v18, 0x3d372713, v14
	v_mul_f32_e32 v18, v18, v14
	v_fma_f32 v18, v18, v14, v14
	v_mul_f32_e32 v18, 0x3f4c422a, v18
	v_mul_f32_e32 v18, -2.0, v18
	v_mul_f32_e32 v18, 0x3fb8aa3b, v18
	v_exp_f32_e32 v18, v18
	s_nop 0
	v_add_f32_e32 v18, 1.0, v18
	v_rcp_f32_e32 v18, v18
	s_nop 0
	v_mul_f32_e32 v14, v18, v14
	v_mul_f32_e32 v14, v15, v14
	v_cvt_pk_bf16_f32 v13, v13, v14
	v_lshl_add_u64 v[14:15], v[86:87], 0, v[16:17]
	global_store_dwordx2 v[14:15], v[12:13], off offset:1024
	s_waitcnt vmcnt(15)
	v_lshlrev_b32_e32 v12, 16, v92
	v_mul_f32_e32 v13, 0x3d372713, v12
	v_mul_f32_e32 v13, v13, v12
	v_fma_f32 v13, v13, v12, v12
	v_mul_f32_e32 v13, 0x3f4c422a, v13
	v_mul_f32_e32 v13, -2.0, v13
	v_mul_f32_e32 v13, 0x3fb8aa3b, v13
	v_exp_f32_e32 v13, v13
	s_nop 0
	v_add_f32_e32 v13, 1.0, v13
	v_rcp_f32_e32 v13, v13
	s_nop 0
	v_mul_f32_e32 v12, v13, v12
	v_mul_f32_e32 v8, v8, v12
	v_and_b32_e32 v12, 0xffff0000, v92
	v_mul_f32_e32 v13, 0x3d372713, v12
	v_mul_f32_e32 v13, v13, v12
	v_fma_f32 v13, v13, v12, v12
	v_mul_f32_e32 v13, 0x3f4c422a, v13
	v_mul_f32_e32 v13, -2.0, v13
	v_mul_f32_e32 v13, 0x3fb8aa3b, v13
	v_exp_f32_e32 v13, v13
	s_nop 0
	v_add_f32_e32 v13, 1.0, v13
	v_rcp_f32_e32 v13, v13
	s_nop 0
	v_mul_f32_e32 v12, v13, v12
	v_mul_f32_e32 v9, v9, v12
	v_cvt_pk_bf16_f32 v8, v8, v9
	v_lshlrev_b32_e32 v9, 16, v93
	v_mul_f32_e32 v12, 0x3d372713, v9
	v_mul_f32_e32 v12, v12, v9
	v_fma_f32 v12, v12, v9, v9
	v_mul_f32_e32 v12, 0x3f4c422a, v12
	v_mul_f32_e32 v12, -2.0, v12
	v_mul_f32_e32 v12, 0x3fb8aa3b, v12
	v_exp_f32_e32 v12, v12
	s_nop 0
	v_add_f32_e32 v12, 1.0, v12
	v_rcp_f32_e32 v12, v12
	s_nop 0
	v_mul_f32_e32 v9, v12, v9
	v_mul_f32_e32 v9, v10, v9
	v_and_b32_e32 v10, 0xffff0000, v93
	v_mul_f32_e32 v12, 0x3d372713, v10
	v_mul_f32_e32 v12, v12, v10
	v_fma_f32 v12, v12, v10, v10
	v_mul_f32_e32 v12, 0x3f4c422a, v12
	v_mul_f32_e32 v12, -2.0, v12
	v_mul_f32_e32 v12, 0x3fb8aa3b, v12
	v_exp_f32_e32 v12, v12
	s_nop 0
	v_add_f32_e32 v12, 1.0, v12
	v_rcp_f32_e32 v12, v12
	s_nop 0
	v_mul_f32_e32 v10, v12, v10
	v_mul_f32_e32 v10, v11, v10
	v_cvt_pk_bf16_f32 v9, v9, v10
	global_store_dwordx2 v[14:15], v[8:9], off offset:1056
	s_waitcnt vmcnt(15)
	v_lshlrev_b32_e32 v8, 16, v90
	v_mul_f32_e32 v9, 0x3d372713, v8
	v_mul_f32_e32 v9, v9, v8
	v_fma_f32 v9, v9, v8, v8
	v_mul_f32_e32 v9, 0x3f4c422a, v9
	v_mul_f32_e32 v9, -2.0, v9
	v_mul_f32_e32 v9, 0x3fb8aa3b, v9
	v_exp_f32_e32 v9, v9
	s_nop 0
	v_add_f32_e32 v9, 1.0, v9
	v_rcp_f32_e32 v9, v9
	s_nop 0
	v_mul_f32_e32 v8, v9, v8
	v_mul_f32_e32 v4, v4, v8
	v_and_b32_e32 v8, 0xffff0000, v90
	v_mul_f32_e32 v9, 0x3d372713, v8
	v_mul_f32_e32 v9, v9, v8
	v_fma_f32 v9, v9, v8, v8
	v_mul_f32_e32 v9, 0x3f4c422a, v9
	v_mul_f32_e32 v9, -2.0, v9
	v_mul_f32_e32 v9, 0x3fb8aa3b, v9
	v_exp_f32_e32 v9, v9
	s_nop 0
	v_add_f32_e32 v9, 1.0, v9
	v_rcp_f32_e32 v9, v9
	s_nop 0
	v_mul_f32_e32 v8, v9, v8
	v_mul_f32_e32 v5, v5, v8
	v_cvt_pk_bf16_f32 v4, v4, v5
	v_lshlrev_b32_e32 v5, 16, v91
	v_mul_f32_e32 v8, 0x3d372713, v5
	v_mul_f32_e32 v8, v8, v5
	v_fma_f32 v8, v8, v5, v5
	v_mul_f32_e32 v8, 0x3f4c422a, v8
	v_mul_f32_e32 v8, -2.0, v8
	v_mul_f32_e32 v8, 0x3fb8aa3b, v8
	v_exp_f32_e32 v8, v8
	s_nop 0
	v_add_f32_e32 v8, 1.0, v8
	v_rcp_f32_e32 v8, v8
	s_nop 0
	v_mul_f32_e32 v5, v8, v5
	v_mul_f32_e32 v5, v6, v5
	v_and_b32_e32 v6, 0xffff0000, v91
	v_mul_f32_e32 v8, 0x3d372713, v6
	v_mul_f32_e32 v8, v8, v6
	v_fma_f32 v8, v8, v6, v6
	v_mul_f32_e32 v8, 0x3f4c422a, v8
	v_mul_f32_e32 v8, -2.0, v8
	v_mul_f32_e32 v8, 0x3fb8aa3b, v8
	v_exp_f32_e32 v8, v8
	s_nop 0
	v_add_f32_e32 v8, 1.0, v8
	v_rcp_f32_e32 v8, v8
	s_nop 0
	v_mul_f32_e32 v6, v8, v6
	v_mul_f32_e32 v6, v7, v6
	v_cvt_pk_bf16_f32 v5, v5, v6
	global_store_dwordx2 v[14:15], v[4:5], off offset:1088
	s_waitcnt vmcnt(15)
	v_lshlrev_b32_e32 v4, 16, v88
	v_mul_f32_e32 v5, 0x3d372713, v4
	v_mul_f32_e32 v5, v5, v4
	v_fma_f32 v5, v5, v4, v4
	v_mul_f32_e32 v5, 0x3f4c422a, v5
	v_mul_f32_e32 v5, -2.0, v5
	v_mul_f32_e32 v5, 0x3fb8aa3b, v5
	v_exp_f32_e32 v5, v5
	s_nop 0
	v_add_f32_e32 v5, 1.0, v5
	v_rcp_f32_e32 v5, v5
	s_nop 0
	v_mul_f32_e32 v4, v5, v4
	v_mul_f32_e32 v0, v0, v4
	v_and_b32_e32 v4, 0xffff0000, v88
	v_mul_f32_e32 v5, 0x3d372713, v4
	v_mul_f32_e32 v5, v5, v4
	v_fma_f32 v5, v5, v4, v4
	v_mul_f32_e32 v5, 0x3f4c422a, v5
	v_mul_f32_e32 v5, -2.0, v5
	v_mul_f32_e32 v5, 0x3fb8aa3b, v5
	v_exp_f32_e32 v5, v5
	s_nop 0
	v_add_f32_e32 v5, 1.0, v5
	v_rcp_f32_e32 v5, v5
	s_nop 0
	v_mul_f32_e32 v4, v5, v4
	v_mul_f32_e32 v1, v1, v4
	v_cvt_pk_bf16_f32 v0, v0, v1
	v_lshlrev_b32_e32 v1, 16, v89
	v_mul_f32_e32 v4, 0x3d372713, v1
	v_mul_f32_e32 v4, v4, v1
	v_fma_f32 v4, v4, v1, v1
	v_mul_f32_e32 v4, 0x3f4c422a, v4
	v_mul_f32_e32 v4, -2.0, v4
	v_mul_f32_e32 v4, 0x3fb8aa3b, v4
	v_exp_f32_e32 v4, v4
	s_nop 0
	v_add_f32_e32 v4, 1.0, v4
	v_rcp_f32_e32 v4, v4
	s_nop 0
	v_mul_f32_e32 v1, v4, v1
	v_mul_f32_e32 v1, v2, v1
	v_and_b32_e32 v2, 0xffff0000, v89
	v_mul_f32_e32 v4, 0x3d372713, v2
	v_mul_f32_e32 v4, v4, v2
	v_fma_f32 v4, v4, v2, v2
	v_mul_f32_e32 v4, 0x3f4c422a, v4
	v_mul_f32_e32 v4, -2.0, v4
	v_mul_f32_e32 v4, 0x3fb8aa3b, v4
	v_exp_f32_e32 v4, v4
	s_nop 0
	v_add_f32_e32 v4, 1.0, v4
	v_rcp_f32_e32 v4, v4
	s_nop 0
	v_mul_f32_e32 v2, v4, v2
	v_mul_f32_e32 v2, v3, v2
	v_cvt_pk_bf16_f32 v1, v1, v2
	global_store_dwordx2 v[14:15], v[0:1], off offset:1120
	s_cbranch_scc1 .LBB0_310
